# output-projection GEMM epilogues: the 16 residual loads per tile issued together with counted waits instead of a load/vmcnt(0)/store ladder (bit-identical)
# speedup vs baseline: 1.0127x; 1.0127x over previous
.LBB0_252:
	s_lshl_b32 s94, s14, 7
	s_ashr_i32 s95, s94, 31
	s_lshl_b32 s96, s15, 7
	s_lshl_b64 s[14:15], s[94:95], 11
	s_add_u32 s28, s36, s14
	s_addc_u32 s29, s37, s15
	s_ashr_i32 s97, s96, 31
	s_lshl_b64 s[14:15], s[96:97], 11
	v_readlane_b32 s52, v245, 37
	v_readlane_b32 s53, v245, 38
	s_add_u32 s14, s52, s14
	s_addc_u32 s15, s53, s15
	v_readfirstlane_b32 s68, v88
	v_mov_b32_e32 v2, s15
	v_mov_b32_e32 v3, s29
	v_mov_b32_e32 v4, s14
	v_mov_b32_e32 v5, s28
	s_add_u32 s98, s28, 0x80
	s_addc_u32 s99, s29, 0
	v_lshl_add_u64 v[72:73], s[28:29], 0, v[64:65]
	s_mov_b32 m0, s68
	v_cndmask_b32_e64 v1, v2, v3, s[4:5]
	v_cndmask_b32_e64 v0, v4, v5, s[4:5]
	v_readfirstlane_b32 s69, v91
	global_load_lds_dwordx4 v[72:73], off
	v_lshl_add_u64 v[74:75], v[0:1], 0, v[66:67]
	s_mov_b32 m0, s69
	v_cndmask_b32_e64 v1, v2, v3, s[6:7]
	v_cndmask_b32_e64 v0, v4, v5, s[6:7]
	v_readfirstlane_b32 s70, v92
	global_load_lds_dwordx4 v[74:75], off
	v_lshl_add_u64 v[76:77], v[0:1], 0, v[68:69]
	s_mov_b32 m0, s70
	v_cndmask_b32_e64 v1, v2, v3, s[8:9]
	v_cndmask_b32_e64 v0, v4, v5, s[8:9]
	v_readfirstlane_b32 s71, v93
	global_load_lds_dwordx4 v[76:77], off
	v_lshl_add_u64 v[78:79], v[0:1], 0, v[70:71]
	s_mov_b32 m0, s71
	v_readfirstlane_b32 s29, v94
	global_load_lds_dwordx4 v[78:79], off
	s_add_u32 s100, s14, 0x80
	s_addc_u32 s101, s15, 0
	v_lshl_add_u64 v[80:81], s[14:15], 0, v[64:65]
	s_mov_b32 m0, s29
	v_readfirstlane_b32 s85, v95
	global_load_lds_dwordx4 v[80:81], off
	v_lshl_add_u64 v[82:83], s[14:15], 0, v[66:67]
	s_mov_b32 m0, s85
	v_readfirstlane_b32 s86, v96
	global_load_lds_dwordx4 v[82:83], off
	v_lshl_add_u64 v[84:85], s[14:15], 0, v[68:69]
	s_mov_b32 m0, s86
	v_readfirstlane_b32 s87, v97
	global_load_lds_dwordx4 v[84:85], off
	v_lshl_add_u64 v[86:87], s[14:15], 0, v[70:71]
	s_mov_b32 m0, s87
	v_readfirstlane_b32 s14, v98
	global_load_lds_dwordx4 v[86:87], off
	s_mov_b32 m0, s14
	v_readfirstlane_b32 s15, v99
	s_waitcnt vmcnt(0)
	s_waitcnt vmcnt(0) lgkmcnt(0)
	s_barrier
	global_load_lds_dwordx4 v64, s[98:99]
	s_mov_b32 m0, s15
	v_readfirstlane_b32 s72, v100
	global_load_lds_dwordx4 v66, s[98:99]
	s_mov_b32 m0, s72
	v_readfirstlane_b32 s73, v101
	global_load_lds_dwordx4 v68, s[98:99]
	s_mov_b32 m0, s73
	v_readfirstlane_b32 s95, v102
	global_load_lds_dwordx4 v70, s[98:99]
	s_mov_b32 m0, s95
	v_readfirstlane_b32 s97, v103
	global_load_lds_dwordx4 v64, s[100:101]
	s_mov_b32 m0, s97
	v_readfirstlane_b32 s28, v104
	global_load_lds_dwordx4 v66, s[100:101]
	s_mov_b32 m0, s28
	v_readfirstlane_b32 s84, v105
	global_load_lds_dwordx4 v68, s[100:101]
	s_mov_b32 m0, s84
	v_readfirstlane_b32 s34, v94
	global_load_lds_dwordx4 v70, s[100:101]
	s_add_u32 s98, s98, 0x80
	s_addc_u32 s99, s99, 0
	s_add_u32 s100, s100, 0x80
	s_addc_u32 s101, s101, 0
	ds_read_b128 v[0:3], v106
	ds_read_b128 v[4:7], v107 offset:16384
	ds_read_b128 v[8:11], v106 offset:4096
	ds_read_b128 v[12:15], v107 offset:20480
	s_waitcnt lgkmcnt(0)
	v_mfma_f32_32x32x16_bf16 v[48:63], v[4:7], v[0:3], 0
	ds_read_b128 v[114:117], v108
	ds_read_b128 v[118:121], v109 offset:16384
	ds_read_b128 v[122:125], v108 offset:4096
	ds_read_b128 v[126:129], v109 offset:20480
	s_mov_b32 m0, s68
	v_readfirstlane_b32 s35, v95
	v_readlane_b32 s54, v245, 39
	v_readlane_b32 s55, v245, 40
	v_readlane_b32 s56, v245, 41
	v_readlane_b32 s57, v245, 42
	v_mfma_f32_32x32x16_bf16 v[32:47], v[12:15], v[0:3], 0
	v_readlane_b32 s58, v245, 43
	v_readlane_b32 s59, v245, 44
	v_readlane_b32 s60, v245, 45
	v_readlane_b32 s61, v245, 46
	v_readlane_b32 s62, v245, 47
	v_readlane_b32 s63, v245, 48
	v_readlane_b32 s64, v245, 49
	v_mfma_f32_32x32x16_bf16 v[16:31], v[4:7], v[8:11], 0
	v_readlane_b32 s65, v245, 50
	v_readlane_b32 s66, v245, 51
	v_readlane_b32 s67, v245, 52
	v_readlane_b32 s52, v245, 5
	v_readlane_b32 s53, v245, 6
	s_add_i32 s13, s13, s33
	v_readlane_b32 s54, v245, 7
	v_mfma_f32_32x32x16_bf16 v[0:15], v[12:15], v[8:11], 0
	v_readlane_b32 s55, v245, 8
	v_readlane_b32 s56, v245, 9
	v_readlane_b32 s57, v245, 10
	v_readlane_b32 s58, v245, 11
	v_readlane_b32 s59, v245, 12
	v_readlane_b32 s60, v245, 13
	v_readlane_b32 s61, v245, 14
	s_waitcnt lgkmcnt(0)
	v_mfma_f32_32x32x16_bf16 v[48:63], v[118:121], v[114:117], v[48:63]
	v_readlane_b32 s62, v245, 15
	v_readlane_b32 s63, v245, 16
	v_readlane_b32 s64, v245, 17
	v_readlane_b32 s65, v245, 18
	v_readlane_b32 s66, v245, 19
	v_readlane_b32 s67, v245, 20
	v_mfma_f32_32x32x16_bf16 v[32:47], v[126:129], v[114:117], v[32:47]
	v_mfma_f32_32x32x16_bf16 v[16:31], v[118:121], v[122:125], v[16:31]
	v_mfma_f32_32x32x16_bf16 v[0:15], v[126:129], v[122:125], v[0:15]
	ds_read_b128 v[114:117], v110
	ds_read_b128 v[118:121], v111 offset:16384
	ds_read_b128 v[122:125], v110 offset:4096
	ds_read_b128 v[126:129], v111 offset:20480
	s_waitcnt lgkmcnt(0)
	v_mfma_f32_32x32x16_bf16 v[48:63], v[118:121], v[114:117], v[48:63]
	v_mfma_f32_32x32x16_bf16 v[32:47], v[126:129], v[114:117], v[32:47]
	v_mfma_f32_32x32x16_bf16 v[16:31], v[118:121], v[122:125], v[16:31]
	v_mfma_f32_32x32x16_bf16 v[0:15], v[126:129], v[122:125], v[0:15]
	ds_read_b128 v[114:117], v112
	ds_read_b128 v[118:121], v113 offset:16384
	ds_read_b128 v[122:125], v112 offset:4096
	ds_read_b128 v[126:129], v113 offset:20480
	s_waitcnt vmcnt(0)
	s_waitcnt vmcnt(0) lgkmcnt(0)
	s_barrier
	v_mfma_f32_32x32x16_bf16 v[48:63], v[118:121], v[114:117], v[48:63]
	v_mfma_f32_32x32x16_bf16 v[32:47], v[126:129], v[114:117], v[32:47]
	global_load_lds_dwordx4 v64, s[98:99]
	s_mov_b32 m0, s69
	s_nop 0
	global_load_lds_dwordx4 v66, s[98:99]
	s_mov_b32 m0, s70
	v_mfma_f32_32x32x16_bf16 v[16:31], v[118:121], v[122:125], v[16:31]
	global_load_lds_dwordx4 v68, s[98:99]
	s_mov_b32 m0, s71
	s_nop 0
	global_load_lds_dwordx4 v70, s[98:99]
	s_mov_b32 m0, s29
	v_mfma_f32_32x32x16_bf16 v[0:15], v[126:129], v[122:125], v[0:15]
	global_load_lds_dwordx4 v64, s[100:101]
	s_mov_b32 m0, s85
	s_nop 0
	global_load_lds_dwordx4 v66, s[100:101]
	s_mov_b32 m0, s86
	s_nop 0
	global_load_lds_dwordx4 v68, s[100:101]
	s_mov_b32 m0, s87
	s_nop 0
	global_load_lds_dwordx4 v70, s[100:101]
	s_add_u32 s98, s98, 0x80
	s_addc_u32 s99, s99, 0
	s_add_u32 s100, s100, 0x80
	s_addc_u32 s101, s101, 0
	ds_read_b128 v[114:117], v106 offset:32768
	ds_read_b128 v[118:121], v107 offset:49152
	ds_read_b128 v[122:125], v106 offset:36864
	ds_read_b128 v[126:129], v107 offset:53248
	s_waitcnt lgkmcnt(0)
	v_mfma_f32_32x32x16_bf16 v[48:63], v[118:121], v[114:117], v[48:63]
	s_mov_b32 m0, s14
	v_mfma_f32_32x32x16_bf16 v[32:47], v[126:129], v[114:117], v[32:47]
	v_mfma_f32_32x32x16_bf16 v[16:31], v[118:121], v[122:125], v[16:31]
	v_mfma_f32_32x32x16_bf16 v[0:15], v[126:129], v[122:125], v[0:15]
	ds_read_b128 v[114:117], v108 offset:32768
	ds_read_b128 v[118:121], v109 offset:49152
	ds_read_b128 v[122:125], v108 offset:36864
	ds_read_b128 v[126:129], v109 offset:53248
	s_waitcnt lgkmcnt(0)
	v_mfma_f32_32x32x16_bf16 v[48:63], v[118:121], v[114:117], v[48:63]
	v_mfma_f32_32x32x16_bf16 v[32:47], v[126:129], v[114:117], v[32:47]
	v_mfma_f32_32x32x16_bf16 v[16:31], v[118:121], v[122:125], v[16:31]
	v_mfma_f32_32x32x16_bf16 v[0:15], v[126:129], v[122:125], v[0:15]
	ds_read_b128 v[114:117], v110 offset:32768
	ds_read_b128 v[118:121], v111 offset:49152
	ds_read_b128 v[122:125], v110 offset:36864
	ds_read_b128 v[126:129], v111 offset:53248
	s_waitcnt lgkmcnt(0)
	v_mfma_f32_32x32x16_bf16 v[48:63], v[118:121], v[114:117], v[48:63]
	v_mfma_f32_32x32x16_bf16 v[32:47], v[126:129], v[114:117], v[32:47]
	v_mfma_f32_32x32x16_bf16 v[16:31], v[118:121], v[122:125], v[16:31]
	v_mfma_f32_32x32x16_bf16 v[0:15], v[126:129], v[122:125], v[0:15]
	ds_read_b128 v[114:117], v112 offset:32768
	ds_read_b128 v[118:121], v113 offset:49152
	ds_read_b128 v[122:125], v112 offset:36864
	ds_read_b128 v[126:129], v113 offset:53248
	s_waitcnt vmcnt(0)
	s_waitcnt vmcnt(0) lgkmcnt(0)
	s_barrier
	v_mfma_f32_32x32x16_bf16 v[48:63], v[118:121], v[114:117], v[48:63]
	v_mfma_f32_32x32x16_bf16 v[32:47], v[126:129], v[114:117], v[32:47]
	global_load_lds_dwordx4 v64, s[98:99]
	s_mov_b32 m0, s15
	s_nop 0
	global_load_lds_dwordx4 v66, s[98:99]
	s_mov_b32 m0, s72
	v_mfma_f32_32x32x16_bf16 v[16:31], v[118:121], v[122:125], v[16:31]
	global_load_lds_dwordx4 v68, s[98:99]
	s_mov_b32 m0, s73
	s_nop 0
	global_load_lds_dwordx4 v70, s[98:99]
	s_mov_b32 m0, s95
	v_mfma_f32_32x32x16_bf16 v[0:15], v[126:129], v[122:125], v[0:15]
	global_load_lds_dwordx4 v64, s[100:101]
	s_mov_b32 m0, s97
	s_nop 0
	global_load_lds_dwordx4 v66, s[100:101]
	s_mov_b32 m0, s28
	s_nop 0
	global_load_lds_dwordx4 v68, s[100:101]
	s_mov_b32 m0, s84
	s_nop 0
	global_load_lds_dwordx4 v70, s[100:101]
	s_add_u32 s98, s98, 0x80
	s_addc_u32 s99, s99, 0
	s_add_u32 s100, s100, 0x80
	s_addc_u32 s101, s101, 0
	ds_read_b128 v[114:117], v106
	ds_read_b128 v[118:121], v107 offset:16384
	ds_read_b128 v[122:125], v106 offset:4096
	ds_read_b128 v[126:129], v107 offset:20480
	s_waitcnt lgkmcnt(0)
	v_mfma_f32_32x32x16_bf16 v[48:63], v[118:121], v[114:117], v[48:63]
	s_mov_b32 m0, s68
	v_mfma_f32_32x32x16_bf16 v[32:47], v[126:129], v[114:117], v[32:47]
	v_mfma_f32_32x32x16_bf16 v[16:31], v[118:121], v[122:125], v[16:31]
	v_mfma_f32_32x32x16_bf16 v[0:15], v[126:129], v[122:125], v[0:15]
	ds_read_b128 v[114:117], v108
	ds_read_b128 v[118:121], v109 offset:16384
	ds_read_b128 v[122:125], v108 offset:4096
	ds_read_b128 v[126:129], v109 offset:20480
	s_waitcnt lgkmcnt(0)
	v_mfma_f32_32x32x16_bf16 v[48:63], v[118:121], v[114:117], v[48:63]
	v_mfma_f32_32x32x16_bf16 v[32:47], v[126:129], v[114:117], v[32:47]
	v_mfma_f32_32x32x16_bf16 v[16:31], v[118:121], v[122:125], v[16:31]
	v_mfma_f32_32x32x16_bf16 v[0:15], v[126:129], v[122:125], v[0:15]
	ds_read_b128 v[114:117], v110
	ds_read_b128 v[118:121], v111 offset:16384
	ds_read_b128 v[122:125], v110 offset:4096
	ds_read_b128 v[126:129], v111 offset:20480
	s_waitcnt lgkmcnt(0)
	v_mfma_f32_32x32x16_bf16 v[48:63], v[118:121], v[114:117], v[48:63]
	v_mfma_f32_32x32x16_bf16 v[32:47], v[126:129], v[114:117], v[32:47]
	v_mfma_f32_32x32x16_bf16 v[16:31], v[118:121], v[122:125], v[16:31]
	v_mfma_f32_32x32x16_bf16 v[0:15], v[126:129], v[122:125], v[0:15]
	ds_read_b128 v[114:117], v112
	ds_read_b128 v[118:121], v113 offset:16384
	ds_read_b128 v[122:125], v112 offset:4096
	ds_read_b128 v[126:129], v113 offset:20480
	s_waitcnt vmcnt(0)
	s_waitcnt vmcnt(0) lgkmcnt(0)
	s_barrier
	v_mfma_f32_32x32x16_bf16 v[48:63], v[118:121], v[114:117], v[48:63]
	v_mfma_f32_32x32x16_bf16 v[32:47], v[126:129], v[114:117], v[32:47]
	global_load_lds_dwordx4 v64, s[98:99]
	s_mov_b32 m0, s69
	s_nop 0
	global_load_lds_dwordx4 v66, s[98:99]
	s_mov_b32 m0, s70
	v_mfma_f32_32x32x16_bf16 v[16:31], v[118:121], v[122:125], v[16:31]
	global_load_lds_dwordx4 v68, s[98:99]
	s_mov_b32 m0, s71
	s_nop 0
	global_load_lds_dwordx4 v70, s[98:99]
	s_mov_b32 m0, s29
	v_mfma_f32_32x32x16_bf16 v[0:15], v[126:129], v[122:125], v[0:15]
	global_load_lds_dwordx4 v64, s[100:101]
	s_mov_b32 m0, s85
	s_nop 0
	global_load_lds_dwordx4 v66, s[100:101]
	s_mov_b32 m0, s86
	s_nop 0
	global_load_lds_dwordx4 v68, s[100:101]
	s_mov_b32 m0, s87
	s_nop 0
	global_load_lds_dwordx4 v70, s[100:101]
	s_add_u32 s98, s98, 0x80
	s_addc_u32 s99, s99, 0
	s_add_u32 s100, s100, 0x80
	s_addc_u32 s101, s101, 0
	ds_read_b128 v[114:117], v106 offset:32768
	ds_read_b128 v[118:121], v107 offset:49152
	ds_read_b128 v[122:125], v106 offset:36864
	ds_read_b128 v[126:129], v107 offset:53248
	s_waitcnt lgkmcnt(0)
	v_mfma_f32_32x32x16_bf16 v[48:63], v[118:121], v[114:117], v[48:63]
	s_mov_b32 m0, s14
	v_mfma_f32_32x32x16_bf16 v[32:47], v[126:129], v[114:117], v[32:47]
	v_mfma_f32_32x32x16_bf16 v[16:31], v[118:121], v[122:125], v[16:31]
	v_mfma_f32_32x32x16_bf16 v[0:15], v[126:129], v[122:125], v[0:15]
	ds_read_b128 v[114:117], v108 offset:32768
	ds_read_b128 v[118:121], v109 offset:49152
	ds_read_b128 v[122:125], v108 offset:36864
	ds_read_b128 v[126:129], v109 offset:53248
	s_waitcnt lgkmcnt(0)
	v_mfma_f32_32x32x16_bf16 v[48:63], v[118:121], v[114:117], v[48:63]
	v_mfma_f32_32x32x16_bf16 v[32:47], v[126:129], v[114:117], v[32:47]
	v_mfma_f32_32x32x16_bf16 v[16:31], v[118:121], v[122:125], v[16:31]
	v_mfma_f32_32x32x16_bf16 v[0:15], v[126:129], v[122:125], v[0:15]
	ds_read_b128 v[114:117], v110 offset:32768
	ds_read_b128 v[118:121], v111 offset:49152
	ds_read_b128 v[122:125], v110 offset:36864
	ds_read_b128 v[126:129], v111 offset:53248
	s_waitcnt lgkmcnt(0)
	v_mfma_f32_32x32x16_bf16 v[48:63], v[118:121], v[114:117], v[48:63]
	v_mfma_f32_32x32x16_bf16 v[32:47], v[126:129], v[114:117], v[32:47]
	v_mfma_f32_32x32x16_bf16 v[16:31], v[118:121], v[122:125], v[16:31]
	v_mfma_f32_32x32x16_bf16 v[0:15], v[126:129], v[122:125], v[0:15]
	ds_read_b128 v[114:117], v112 offset:32768
	ds_read_b128 v[118:121], v113 offset:49152
	ds_read_b128 v[122:125], v112 offset:36864
	ds_read_b128 v[126:129], v113 offset:53248
	s_waitcnt vmcnt(0)
	s_waitcnt vmcnt(0) lgkmcnt(0)
	s_barrier
	v_mfma_f32_32x32x16_bf16 v[48:63], v[118:121], v[114:117], v[48:63]
	v_mfma_f32_32x32x16_bf16 v[32:47], v[126:129], v[114:117], v[32:47]
	global_load_lds_dwordx4 v64, s[98:99]
	s_mov_b32 m0, s15
	s_nop 0
	global_load_lds_dwordx4 v66, s[98:99]
	s_mov_b32 m0, s72
	v_mfma_f32_32x32x16_bf16 v[16:31], v[118:121], v[122:125], v[16:31]
	global_load_lds_dwordx4 v68, s[98:99]
	s_mov_b32 m0, s73
	s_nop 0
	global_load_lds_dwordx4 v70, s[98:99]
	s_mov_b32 m0, s95
	v_mfma_f32_32x32x16_bf16 v[0:15], v[126:129], v[122:125], v[0:15]
	global_load_lds_dwordx4 v64, s[100:101]
	s_mov_b32 m0, s97
	s_nop 0
	global_load_lds_dwordx4 v66, s[100:101]
	s_mov_b32 m0, s28
	s_nop 0
	global_load_lds_dwordx4 v68, s[100:101]
	s_mov_b32 m0, s84
	s_nop 0
	global_load_lds_dwordx4 v70, s[100:101]
	s_add_u32 s98, s98, 0x80
	s_addc_u32 s99, s99, 0
	s_add_u32 s100, s100, 0x80
	s_addc_u32 s101, s101, 0
	ds_read_b128 v[114:117], v106
	ds_read_b128 v[118:121], v107 offset:16384
	ds_read_b128 v[122:125], v106 offset:4096
	ds_read_b128 v[126:129], v107 offset:20480
	s_waitcnt lgkmcnt(0)
	v_mfma_f32_32x32x16_bf16 v[48:63], v[118:121], v[114:117], v[48:63]
	s_mov_b32 m0, s68
	v_mfma_f32_32x32x16_bf16 v[32:47], v[126:129], v[114:117], v[32:47]
	v_mfma_f32_32x32x16_bf16 v[16:31], v[118:121], v[122:125], v[16:31]
	v_mfma_f32_32x32x16_bf16 v[0:15], v[126:129], v[122:125], v[0:15]
	ds_read_b128 v[114:117], v108
	ds_read_b128 v[118:121], v109 offset:16384
	ds_read_b128 v[122:125], v108 offset:4096
	ds_read_b128 v[126:129], v109 offset:20480
	s_waitcnt lgkmcnt(0)
	v_mfma_f32_32x32x16_bf16 v[48:63], v[118:121], v[114:117], v[48:63]
	v_mfma_f32_32x32x16_bf16 v[32:47], v[126:129], v[114:117], v[32:47]
	v_mfma_f32_32x32x16_bf16 v[16:31], v[118:121], v[122:125], v[16:31]
	v_mfma_f32_32x32x16_bf16 v[0:15], v[126:129], v[122:125], v[0:15]
	ds_read_b128 v[114:117], v110
	ds_read_b128 v[118:121], v111 offset:16384
	ds_read_b128 v[122:125], v110 offset:4096
	ds_read_b128 v[126:129], v111 offset:20480
	s_waitcnt lgkmcnt(0)
	v_mfma_f32_32x32x16_bf16 v[48:63], v[118:121], v[114:117], v[48:63]
	v_mfma_f32_32x32x16_bf16 v[32:47], v[126:129], v[114:117], v[32:47]
	v_mfma_f32_32x32x16_bf16 v[16:31], v[118:121], v[122:125], v[16:31]
	v_mfma_f32_32x32x16_bf16 v[0:15], v[126:129], v[122:125], v[0:15]
	ds_read_b128 v[114:117], v112
	ds_read_b128 v[118:121], v113 offset:16384
	ds_read_b128 v[122:125], v112 offset:4096
	ds_read_b128 v[126:129], v113 offset:20480
	s_waitcnt vmcnt(0)
	s_waitcnt vmcnt(0) lgkmcnt(0)
	s_barrier
	v_mfma_f32_32x32x16_bf16 v[48:63], v[118:121], v[114:117], v[48:63]
	v_mfma_f32_32x32x16_bf16 v[32:47], v[126:129], v[114:117], v[32:47]
	global_load_lds_dwordx4 v64, s[98:99]
	s_mov_b32 m0, s69
	s_nop 0
	global_load_lds_dwordx4 v66, s[98:99]
	s_mov_b32 m0, s70
	v_mfma_f32_32x32x16_bf16 v[16:31], v[118:121], v[122:125], v[16:31]
	global_load_lds_dwordx4 v68, s[98:99]
	s_mov_b32 m0, s71
	s_nop 0
	global_load_lds_dwordx4 v70, s[98:99]
	s_mov_b32 m0, s29
	v_mfma_f32_32x32x16_bf16 v[0:15], v[126:129], v[122:125], v[0:15]
	global_load_lds_dwordx4 v64, s[100:101]
	s_mov_b32 m0, s85
	s_nop 0
	global_load_lds_dwordx4 v66, s[100:101]
	s_mov_b32 m0, s86
	s_nop 0
	global_load_lds_dwordx4 v68, s[100:101]
	s_mov_b32 m0, s87
	s_nop 0
	global_load_lds_dwordx4 v70, s[100:101]
	s_add_u32 s98, s98, 0x80
	s_addc_u32 s99, s99, 0
	s_add_u32 s100, s100, 0x80
	s_addc_u32 s101, s101, 0
	ds_read_b128 v[114:117], v106 offset:32768
	ds_read_b128 v[118:121], v107 offset:49152
	ds_read_b128 v[122:125], v106 offset:36864
	ds_read_b128 v[126:129], v107 offset:53248
	s_waitcnt lgkmcnt(0)
	v_mfma_f32_32x32x16_bf16 v[48:63], v[118:121], v[114:117], v[48:63]
	s_mov_b32 m0, s14
	v_mfma_f32_32x32x16_bf16 v[32:47], v[126:129], v[114:117], v[32:47]
	v_mfma_f32_32x32x16_bf16 v[16:31], v[118:121], v[122:125], v[16:31]
	v_mfma_f32_32x32x16_bf16 v[0:15], v[126:129], v[122:125], v[0:15]
	ds_read_b128 v[114:117], v108 offset:32768
	ds_read_b128 v[118:121], v109 offset:49152
	ds_read_b128 v[122:125], v108 offset:36864
	ds_read_b128 v[126:129], v109 offset:53248
	s_waitcnt lgkmcnt(0)
	v_mfma_f32_32x32x16_bf16 v[48:63], v[118:121], v[114:117], v[48:63]
	v_mfma_f32_32x32x16_bf16 v[32:47], v[126:129], v[114:117], v[32:47]
	v_mfma_f32_32x32x16_bf16 v[16:31], v[118:121], v[122:125], v[16:31]
	v_mfma_f32_32x32x16_bf16 v[0:15], v[126:129], v[122:125], v[0:15]
	ds_read_b128 v[114:117], v110 offset:32768
	ds_read_b128 v[118:121], v111 offset:49152
	ds_read_b128 v[122:125], v110 offset:36864
	ds_read_b128 v[126:129], v111 offset:53248
	s_waitcnt lgkmcnt(0)
	v_mfma_f32_32x32x16_bf16 v[48:63], v[118:121], v[114:117], v[48:63]
	v_mfma_f32_32x32x16_bf16 v[32:47], v[126:129], v[114:117], v[32:47]
	v_mfma_f32_32x32x16_bf16 v[16:31], v[118:121], v[122:125], v[16:31]
	v_mfma_f32_32x32x16_bf16 v[0:15], v[126:129], v[122:125], v[0:15]
	ds_read_b128 v[114:117], v112 offset:32768
	ds_read_b128 v[118:121], v113 offset:49152
	ds_read_b128 v[122:125], v112 offset:36864
	ds_read_b128 v[126:129], v113 offset:53248
	s_waitcnt vmcnt(0)
	s_waitcnt vmcnt(0) lgkmcnt(0)
	s_barrier
	v_mfma_f32_32x32x16_bf16 v[48:63], v[118:121], v[114:117], v[48:63]
	v_mfma_f32_32x32x16_bf16 v[32:47], v[126:129], v[114:117], v[32:47]
	global_load_lds_dwordx4 v64, s[98:99]
	s_mov_b32 m0, s15
	s_nop 0
	global_load_lds_dwordx4 v66, s[98:99]
	s_mov_b32 m0, s72
	v_mfma_f32_32x32x16_bf16 v[16:31], v[118:121], v[122:125], v[16:31]
	global_load_lds_dwordx4 v68, s[98:99]
	s_mov_b32 m0, s73
	s_nop 0
	global_load_lds_dwordx4 v70, s[98:99]
	s_mov_b32 m0, s95
	v_mfma_f32_32x32x16_bf16 v[0:15], v[126:129], v[122:125], v[0:15]
	global_load_lds_dwordx4 v64, s[100:101]
	s_mov_b32 m0, s97
	s_nop 0
	global_load_lds_dwordx4 v66, s[100:101]
	s_mov_b32 m0, s28
	s_nop 0
	global_load_lds_dwordx4 v68, s[100:101]
	s_mov_b32 m0, s84
	s_nop 0
	global_load_lds_dwordx4 v70, s[100:101]
	s_add_u32 s98, s98, 0x80
	s_addc_u32 s99, s99, 0
	s_add_u32 s100, s100, 0x80
	s_addc_u32 s101, s101, 0
	ds_read_b128 v[114:117], v106
	ds_read_b128 v[118:121], v107 offset:16384
	ds_read_b128 v[122:125], v106 offset:4096
	ds_read_b128 v[126:129], v107 offset:20480
	s_waitcnt lgkmcnt(0)
	v_mfma_f32_32x32x16_bf16 v[48:63], v[118:121], v[114:117], v[48:63]
	s_mov_b32 m0, s68
	v_readfirstlane_b32 s68, v96
	v_mfma_f32_32x32x16_bf16 v[32:47], v[126:129], v[114:117], v[32:47]
	v_mfma_f32_32x32x16_bf16 v[16:31], v[118:121], v[122:125], v[16:31]
	v_mfma_f32_32x32x16_bf16 v[0:15], v[126:129], v[122:125], v[0:15]
	ds_read_b128 v[114:117], v108
	ds_read_b128 v[118:121], v109 offset:16384
	ds_read_b128 v[122:125], v108 offset:4096
	ds_read_b128 v[126:129], v109 offset:20480
	s_waitcnt lgkmcnt(0)
	v_mfma_f32_32x32x16_bf16 v[48:63], v[118:121], v[114:117], v[48:63]
	v_mfma_f32_32x32x16_bf16 v[32:47], v[126:129], v[114:117], v[32:47]
	v_mfma_f32_32x32x16_bf16 v[16:31], v[118:121], v[122:125], v[16:31]
	v_mfma_f32_32x32x16_bf16 v[0:15], v[126:129], v[122:125], v[0:15]
	ds_read_b128 v[114:117], v110
	ds_read_b128 v[118:121], v111 offset:16384
	ds_read_b128 v[122:125], v110 offset:4096
	ds_read_b128 v[126:129], v111 offset:20480
	s_waitcnt lgkmcnt(0)
	v_mfma_f32_32x32x16_bf16 v[48:63], v[118:121], v[114:117], v[48:63]
	v_mfma_f32_32x32x16_bf16 v[32:47], v[126:129], v[114:117], v[32:47]
	v_mfma_f32_32x32x16_bf16 v[16:31], v[118:121], v[122:125], v[16:31]
	v_mfma_f32_32x32x16_bf16 v[0:15], v[126:129], v[122:125], v[0:15]
	ds_read_b128 v[114:117], v112
	ds_read_b128 v[118:121], v113 offset:16384
	ds_read_b128 v[122:125], v112 offset:4096
	ds_read_b128 v[126:129], v113 offset:20480
	s_waitcnt vmcnt(0)
	s_waitcnt vmcnt(0) lgkmcnt(0)
	s_barrier
	v_mfma_f32_32x32x16_bf16 v[48:63], v[118:121], v[114:117], v[48:63]
	v_mfma_f32_32x32x16_bf16 v[32:47], v[126:129], v[114:117], v[32:47]
	global_load_lds_dwordx4 v64, s[98:99]
	s_mov_b32 m0, s69
	v_readfirstlane_b32 s69, v97
	global_load_lds_dwordx4 v66, s[98:99]
	s_mov_b32 m0, s70
	v_mfma_f32_32x32x16_bf16 v[16:31], v[118:121], v[122:125], v[16:31]
	global_load_lds_dwordx4 v68, s[98:99]
	s_mov_b32 m0, s71
	v_readfirstlane_b32 s70, v98
	global_load_lds_dwordx4 v70, s[98:99]
	s_mov_b32 m0, s29
	v_mfma_f32_32x32x16_bf16 v[0:15], v[126:129], v[122:125], v[0:15]
	global_load_lds_dwordx4 v64, s[100:101]
	s_mov_b32 m0, s85
	v_readfirstlane_b32 s29, v93
	global_load_lds_dwordx4 v66, s[100:101]
	s_mov_b32 m0, s86
	v_readfirstlane_b32 s71, v99
	global_load_lds_dwordx4 v68, s[100:101]
	s_mov_b32 m0, s87
	v_readfirstlane_b32 s85, v103
	global_load_lds_dwordx4 v70, s[100:101]
	s_add_u32 s98, s98, 0x80
	s_addc_u32 s99, s99, 0
	s_add_u32 s100, s100, 0x80
	s_addc_u32 s101, s101, 0
	ds_read_b128 v[114:117], v106 offset:32768
	ds_read_b128 v[118:121], v107 offset:49152
	ds_read_b128 v[122:125], v106 offset:36864
	ds_read_b128 v[126:129], v107 offset:53248
	s_waitcnt lgkmcnt(0)
	v_mfma_f32_32x32x16_bf16 v[48:63], v[118:121], v[114:117], v[48:63]
	s_mov_b32 m0, s14
	v_readfirstlane_b32 s14, v88
	v_readfirstlane_b32 s86, v104
	v_readfirstlane_b32 s87, v105
	v_mfma_f32_32x32x16_bf16 v[32:47], v[126:129], v[114:117], v[32:47]
	v_mfma_f32_32x32x16_bf16 v[16:31], v[118:121], v[122:125], v[16:31]
	v_mfma_f32_32x32x16_bf16 v[0:15], v[126:129], v[122:125], v[0:15]
	ds_read_b128 v[114:117], v108 offset:32768
	ds_read_b128 v[118:121], v109 offset:49152
	ds_read_b128 v[122:125], v108 offset:36864
	ds_read_b128 v[126:129], v109 offset:53248
	s_waitcnt lgkmcnt(0)
	v_mfma_f32_32x32x16_bf16 v[48:63], v[118:121], v[114:117], v[48:63]
	v_mfma_f32_32x32x16_bf16 v[32:47], v[126:129], v[114:117], v[32:47]
	v_mfma_f32_32x32x16_bf16 v[16:31], v[118:121], v[122:125], v[16:31]
	v_mfma_f32_32x32x16_bf16 v[0:15], v[126:129], v[122:125], v[0:15]
	ds_read_b128 v[114:117], v110 offset:32768
	ds_read_b128 v[118:121], v111 offset:49152
	ds_read_b128 v[122:125], v110 offset:36864
	ds_read_b128 v[126:129], v111 offset:53248
	s_waitcnt lgkmcnt(0)
	v_mfma_f32_32x32x16_bf16 v[48:63], v[118:121], v[114:117], v[48:63]
	v_mfma_f32_32x32x16_bf16 v[32:47], v[126:129], v[114:117], v[32:47]
	v_mfma_f32_32x32x16_bf16 v[16:31], v[118:121], v[122:125], v[16:31]
	v_mfma_f32_32x32x16_bf16 v[0:15], v[126:129], v[122:125], v[0:15]
	ds_read_b128 v[114:117], v112 offset:32768
	ds_read_b128 v[118:121], v113 offset:49152
	ds_read_b128 v[122:125], v112 offset:36864
	ds_read_b128 v[126:129], v113 offset:53248
	s_waitcnt vmcnt(0)
	s_waitcnt vmcnt(0) lgkmcnt(0)
	s_barrier
	v_mfma_f32_32x32x16_bf16 v[48:63], v[118:121], v[114:117], v[48:63]
	v_mfma_f32_32x32x16_bf16 v[32:47], v[126:129], v[114:117], v[32:47]
	global_load_lds_dwordx4 v64, s[98:99]
	s_mov_b32 m0, s15
	v_readfirstlane_b32 s15, v91
	global_load_lds_dwordx4 v66, s[98:99]
	s_mov_b32 m0, s72
	v_mfma_f32_32x32x16_bf16 v[16:31], v[118:121], v[122:125], v[16:31]
	global_load_lds_dwordx4 v68, s[98:99]
	s_mov_b32 m0, s73
	v_readfirstlane_b32 s72, v100
	global_load_lds_dwordx4 v70, s[98:99]
	s_mov_b32 m0, s95
	v_mfma_f32_32x32x16_bf16 v[0:15], v[126:129], v[122:125], v[0:15]
	global_load_lds_dwordx4 v64, s[100:101]
	s_mov_b32 m0, s97
	v_readfirstlane_b32 s73, v101
	global_load_lds_dwordx4 v66, s[100:101]
	s_mov_b32 m0, s28
	v_readfirstlane_b32 s28, v92
	global_load_lds_dwordx4 v68, s[100:101]
	s_mov_b32 m0, s84
	v_readfirstlane_b32 s84, v102
	global_load_lds_dwordx4 v70, s[100:101]
	s_add_u32 s98, s98, 0x80
	s_addc_u32 s99, s99, 0
	s_add_u32 s100, s100, 0x80
	s_addc_u32 s101, s101, 0
	ds_read_b128 v[114:117], v106
	ds_read_b128 v[118:121], v107 offset:16384
	ds_read_b128 v[122:125], v106 offset:4096
	ds_read_b128 v[126:129], v107 offset:20480
	s_waitcnt lgkmcnt(0)
	v_mfma_f32_32x32x16_bf16 v[48:63], v[118:121], v[114:117], v[48:63]
	s_mov_b32 m0, s14
	v_mfma_f32_32x32x16_bf16 v[32:47], v[126:129], v[114:117], v[32:47]
	v_mfma_f32_32x32x16_bf16 v[16:31], v[118:121], v[122:125], v[16:31]
	v_mfma_f32_32x32x16_bf16 v[0:15], v[126:129], v[122:125], v[0:15]
	ds_read_b128 v[114:117], v108
	ds_read_b128 v[118:121], v109 offset:16384
	ds_read_b128 v[122:125], v108 offset:4096
	ds_read_b128 v[126:129], v109 offset:20480
	s_waitcnt lgkmcnt(0)
	v_mfma_f32_32x32x16_bf16 v[48:63], v[118:121], v[114:117], v[48:63]
	v_mfma_f32_32x32x16_bf16 v[32:47], v[126:129], v[114:117], v[32:47]
	v_mfma_f32_32x32x16_bf16 v[16:31], v[118:121], v[122:125], v[16:31]
	v_mfma_f32_32x32x16_bf16 v[0:15], v[126:129], v[122:125], v[0:15]
	ds_read_b128 v[114:117], v110
	ds_read_b128 v[118:121], v111 offset:16384
	ds_read_b128 v[122:125], v110 offset:4096
	ds_read_b128 v[126:129], v111 offset:20480
	s_waitcnt lgkmcnt(0)
	v_mfma_f32_32x32x16_bf16 v[48:63], v[118:121], v[114:117], v[48:63]
	v_mfma_f32_32x32x16_bf16 v[32:47], v[126:129], v[114:117], v[32:47]
	v_mfma_f32_32x32x16_bf16 v[16:31], v[118:121], v[122:125], v[16:31]
	v_mfma_f32_32x32x16_bf16 v[0:15], v[126:129], v[122:125], v[0:15]
	ds_read_b128 v[114:117], v112
	ds_read_b128 v[118:121], v113 offset:16384
	ds_read_b128 v[122:125], v112 offset:4096
	ds_read_b128 v[126:129], v113 offset:20480
	s_waitcnt vmcnt(0)
	s_waitcnt vmcnt(0) lgkmcnt(0)
	s_barrier
	v_mfma_f32_32x32x16_bf16 v[48:63], v[118:121], v[114:117], v[48:63]
	v_mfma_f32_32x32x16_bf16 v[32:47], v[126:129], v[114:117], v[32:47]
	global_load_lds_dwordx4 v64, s[98:99]
	s_mov_b32 m0, s15
	s_nop 0
	global_load_lds_dwordx4 v66, s[98:99]
	s_mov_b32 m0, s28
	v_mfma_f32_32x32x16_bf16 v[16:31], v[118:121], v[122:125], v[16:31]
	global_load_lds_dwordx4 v68, s[98:99]
	s_mov_b32 m0, s29
	s_nop 0
	global_load_lds_dwordx4 v70, s[98:99]
	s_mov_b32 m0, s34
	v_mfma_f32_32x32x16_bf16 v[0:15], v[126:129], v[122:125], v[0:15]
	global_load_lds_dwordx4 v64, s[100:101]
	s_mov_b32 m0, s35
	s_nop 0
	global_load_lds_dwordx4 v66, s[100:101]
	s_mov_b32 m0, s68
	s_nop 0
	global_load_lds_dwordx4 v68, s[100:101]
	s_mov_b32 m0, s69
	s_nop 0
	global_load_lds_dwordx4 v70, s[100:101]
	s_add_u32 s98, s98, 0x80
	s_addc_u32 s99, s99, 0
	s_add_u32 s100, s100, 0x80
	s_addc_u32 s101, s101, 0
	ds_read_b128 v[114:117], v106 offset:32768
	ds_read_b128 v[118:121], v107 offset:49152
	ds_read_b128 v[122:125], v106 offset:36864
	ds_read_b128 v[126:129], v107 offset:53248
	s_waitcnt lgkmcnt(0)
	v_mfma_f32_32x32x16_bf16 v[48:63], v[118:121], v[114:117], v[48:63]
	s_mov_b32 m0, s70
	v_mfma_f32_32x32x16_bf16 v[32:47], v[126:129], v[114:117], v[32:47]
	v_mfma_f32_32x32x16_bf16 v[16:31], v[118:121], v[122:125], v[16:31]
	v_mfma_f32_32x32x16_bf16 v[0:15], v[126:129], v[122:125], v[0:15]
	ds_read_b128 v[114:117], v108 offset:32768
	ds_read_b128 v[118:121], v109 offset:49152
	ds_read_b128 v[122:125], v108 offset:36864
	ds_read_b128 v[126:129], v109 offset:53248
	s_waitcnt lgkmcnt(0)
	v_mfma_f32_32x32x16_bf16 v[48:63], v[118:121], v[114:117], v[48:63]
	v_mfma_f32_32x32x16_bf16 v[32:47], v[126:129], v[114:117], v[32:47]
	v_mfma_f32_32x32x16_bf16 v[16:31], v[118:121], v[122:125], v[16:31]
	v_mfma_f32_32x32x16_bf16 v[0:15], v[126:129], v[122:125], v[0:15]
	ds_read_b128 v[114:117], v110 offset:32768
	ds_read_b128 v[118:121], v111 offset:49152
	ds_read_b128 v[122:125], v110 offset:36864
	ds_read_b128 v[126:129], v111 offset:53248
	s_waitcnt lgkmcnt(0)
	v_mfma_f32_32x32x16_bf16 v[48:63], v[118:121], v[114:117], v[48:63]
	v_mfma_f32_32x32x16_bf16 v[32:47], v[126:129], v[114:117], v[32:47]
	v_mfma_f32_32x32x16_bf16 v[16:31], v[118:121], v[122:125], v[16:31]
	v_mfma_f32_32x32x16_bf16 v[0:15], v[126:129], v[122:125], v[0:15]
	ds_read_b128 v[114:117], v112 offset:32768
	ds_read_b128 v[118:121], v113 offset:49152
	ds_read_b128 v[122:125], v112 offset:36864
	ds_read_b128 v[126:129], v113 offset:53248
	s_waitcnt vmcnt(0)
	s_waitcnt vmcnt(0) lgkmcnt(0)
	s_barrier
	v_mfma_f32_32x32x16_bf16 v[48:63], v[118:121], v[114:117], v[48:63]
	v_mfma_f32_32x32x16_bf16 v[32:47], v[126:129], v[114:117], v[32:47]
	global_load_lds_dwordx4 v64, s[98:99]
	s_mov_b32 m0, s71
	s_nop 0
	global_load_lds_dwordx4 v66, s[98:99]
	s_mov_b32 m0, s72
	v_mfma_f32_32x32x16_bf16 v[16:31], v[118:121], v[122:125], v[16:31]
	global_load_lds_dwordx4 v68, s[98:99]
	s_mov_b32 m0, s73
	s_nop 0
	global_load_lds_dwordx4 v70, s[98:99]
	s_mov_b32 m0, s84
	v_mfma_f32_32x32x16_bf16 v[0:15], v[126:129], v[122:125], v[0:15]
	global_load_lds_dwordx4 v64, s[100:101]
	s_mov_b32 m0, s85
	s_nop 0
	global_load_lds_dwordx4 v66, s[100:101]
	s_mov_b32 m0, s86
	s_nop 0
	global_load_lds_dwordx4 v68, s[100:101]
	s_mov_b32 m0, s87
	s_nop 0
	global_load_lds_dwordx4 v70, s[100:101]
	s_add_u32 s98, s98, 0x80
	s_addc_u32 s99, s99, 0
	s_add_u32 s100, s100, 0x80
	s_addc_u32 s101, s101, 0
	ds_read_b128 v[114:117], v106
	ds_read_b128 v[118:121], v107 offset:16384
	ds_read_b128 v[122:125], v106 offset:4096
	ds_read_b128 v[126:129], v107 offset:20480
	s_waitcnt lgkmcnt(0)
	v_mfma_f32_32x32x16_bf16 v[48:63], v[118:121], v[114:117], v[48:63]
	s_mov_b32 m0, s14
	v_mfma_f32_32x32x16_bf16 v[32:47], v[126:129], v[114:117], v[32:47]
	v_mfma_f32_32x32x16_bf16 v[16:31], v[118:121], v[122:125], v[16:31]
	v_mfma_f32_32x32x16_bf16 v[0:15], v[126:129], v[122:125], v[0:15]
	ds_read_b128 v[114:117], v108
	ds_read_b128 v[118:121], v109 offset:16384
	ds_read_b128 v[122:125], v108 offset:4096
	ds_read_b128 v[126:129], v109 offset:20480
	s_waitcnt lgkmcnt(0)
	v_mfma_f32_32x32x16_bf16 v[48:63], v[118:121], v[114:117], v[48:63]
	v_mfma_f32_32x32x16_bf16 v[32:47], v[126:129], v[114:117], v[32:47]
	v_mfma_f32_32x32x16_bf16 v[16:31], v[118:121], v[122:125], v[16:31]
	v_mfma_f32_32x32x16_bf16 v[0:15], v[126:129], v[122:125], v[0:15]
	ds_read_b128 v[114:117], v110
	ds_read_b128 v[118:121], v111 offset:16384
	ds_read_b128 v[122:125], v110 offset:4096
	ds_read_b128 v[126:129], v111 offset:20480
	s_waitcnt lgkmcnt(0)
	v_mfma_f32_32x32x16_bf16 v[48:63], v[118:121], v[114:117], v[48:63]
	v_mfma_f32_32x32x16_bf16 v[32:47], v[126:129], v[114:117], v[32:47]
	v_mfma_f32_32x32x16_bf16 v[16:31], v[118:121], v[122:125], v[16:31]
	v_mfma_f32_32x32x16_bf16 v[0:15], v[126:129], v[122:125], v[0:15]
	ds_read_b128 v[114:117], v112
	ds_read_b128 v[118:121], v113 offset:16384
	ds_read_b128 v[122:125], v112 offset:4096
	ds_read_b128 v[126:129], v113 offset:20480
	s_waitcnt vmcnt(0)
	s_waitcnt vmcnt(0) lgkmcnt(0)
	s_barrier
	v_mfma_f32_32x32x16_bf16 v[48:63], v[118:121], v[114:117], v[48:63]
	v_mfma_f32_32x32x16_bf16 v[32:47], v[126:129], v[114:117], v[32:47]
	global_load_lds_dwordx4 v64, s[98:99]
	s_mov_b32 m0, s15
	s_nop 0
	global_load_lds_dwordx4 v66, s[98:99]
	s_mov_b32 m0, s28
	v_mfma_f32_32x32x16_bf16 v[16:31], v[118:121], v[122:125], v[16:31]
	global_load_lds_dwordx4 v68, s[98:99]
	s_mov_b32 m0, s29
	s_nop 0
	global_load_lds_dwordx4 v70, s[98:99]
	s_mov_b32 m0, s34
	v_mfma_f32_32x32x16_bf16 v[0:15], v[126:129], v[122:125], v[0:15]
	global_load_lds_dwordx4 v64, s[100:101]
	s_mov_b32 m0, s35
	s_nop 0
	global_load_lds_dwordx4 v66, s[100:101]
	s_mov_b32 m0, s68
	s_nop 0
	global_load_lds_dwordx4 v68, s[100:101]
	s_mov_b32 m0, s69
	s_nop 0
	global_load_lds_dwordx4 v70, s[100:101]
	s_add_u32 s98, s98, 0x80
	s_addc_u32 s99, s99, 0
	s_add_u32 s100, s100, 0x80
	s_addc_u32 s101, s101, 0
	ds_read_b128 v[114:117], v106 offset:32768
	ds_read_b128 v[118:121], v107 offset:49152
	ds_read_b128 v[122:125], v106 offset:36864
	ds_read_b128 v[126:129], v107 offset:53248
	s_waitcnt lgkmcnt(0)
	v_mfma_f32_32x32x16_bf16 v[48:63], v[118:121], v[114:117], v[48:63]
	s_mov_b32 m0, s70
	v_mfma_f32_32x32x16_bf16 v[32:47], v[126:129], v[114:117], v[32:47]
	v_mfma_f32_32x32x16_bf16 v[16:31], v[118:121], v[122:125], v[16:31]
	v_mfma_f32_32x32x16_bf16 v[0:15], v[126:129], v[122:125], v[0:15]
	ds_read_b128 v[114:117], v108 offset:32768
	ds_read_b128 v[118:121], v109 offset:49152
	ds_read_b128 v[122:125], v108 offset:36864
	ds_read_b128 v[126:129], v109 offset:53248
	s_waitcnt lgkmcnt(0)
	v_mfma_f32_32x32x16_bf16 v[48:63], v[118:121], v[114:117], v[48:63]
	v_mfma_f32_32x32x16_bf16 v[32:47], v[126:129], v[114:117], v[32:47]
	v_mfma_f32_32x32x16_bf16 v[16:31], v[118:121], v[122:125], v[16:31]
	v_mfma_f32_32x32x16_bf16 v[0:15], v[126:129], v[122:125], v[0:15]
	ds_read_b128 v[114:117], v110 offset:32768
	ds_read_b128 v[118:121], v111 offset:49152
	ds_read_b128 v[122:125], v110 offset:36864
	ds_read_b128 v[126:129], v111 offset:53248
	s_waitcnt lgkmcnt(0)
	v_mfma_f32_32x32x16_bf16 v[48:63], v[118:121], v[114:117], v[48:63]
	v_mfma_f32_32x32x16_bf16 v[32:47], v[126:129], v[114:117], v[32:47]
	v_mfma_f32_32x32x16_bf16 v[16:31], v[118:121], v[122:125], v[16:31]
	v_mfma_f32_32x32x16_bf16 v[0:15], v[126:129], v[122:125], v[0:15]
	ds_read_b128 v[114:117], v112 offset:32768
	ds_read_b128 v[118:121], v113 offset:49152
	ds_read_b128 v[122:125], v112 offset:36864
	ds_read_b128 v[126:129], v113 offset:53248
	s_waitcnt vmcnt(0)
	s_waitcnt vmcnt(0) lgkmcnt(0)
	s_barrier
	v_mfma_f32_32x32x16_bf16 v[48:63], v[118:121], v[114:117], v[48:63]
	v_mfma_f32_32x32x16_bf16 v[32:47], v[126:129], v[114:117], v[32:47]
	global_load_lds_dwordx4 v64, s[98:99]
	s_mov_b32 m0, s71
	s_nop 0
	global_load_lds_dwordx4 v66, s[98:99]
	s_mov_b32 m0, s72
	v_mfma_f32_32x32x16_bf16 v[16:31], v[118:121], v[122:125], v[16:31]
	global_load_lds_dwordx4 v68, s[98:99]
	s_mov_b32 m0, s73
	s_nop 0
	global_load_lds_dwordx4 v70, s[98:99]
	s_mov_b32 m0, s84
	v_mfma_f32_32x32x16_bf16 v[0:15], v[126:129], v[122:125], v[0:15]
	global_load_lds_dwordx4 v64, s[100:101]
	s_mov_b32 m0, s85
	s_nop 0
	global_load_lds_dwordx4 v66, s[100:101]
	s_mov_b32 m0, s86
	s_nop 0
	global_load_lds_dwordx4 v68, s[100:101]
	s_mov_b32 m0, s87
	s_nop 0
	global_load_lds_dwordx4 v70, s[100:101]
	s_add_u32 s98, s98, 0x80
	s_addc_u32 s99, s99, 0
	s_add_u32 s100, s100, 0x80
	s_addc_u32 s101, s101, 0
	ds_read_b128 v[114:117], v106
	ds_read_b128 v[118:121], v107 offset:16384
	ds_read_b128 v[122:125], v106 offset:4096
	ds_read_b128 v[126:129], v107 offset:20480
	s_waitcnt lgkmcnt(0)
	v_mfma_f32_32x32x16_bf16 v[48:63], v[118:121], v[114:117], v[48:63]
	s_mov_b32 m0, s14
	s_add_i32 s14, s2, s13
	s_cmpk_lt_i32 s14, 0x400
	v_mfma_f32_32x32x16_bf16 v[32:47], v[126:129], v[114:117], v[32:47]
	v_mfma_f32_32x32x16_bf16 v[16:31], v[118:121], v[122:125], v[16:31]
	v_mfma_f32_32x32x16_bf16 v[0:15], v[126:129], v[122:125], v[0:15]
	ds_read_b128 v[114:117], v108
	ds_read_b128 v[118:121], v109 offset:16384
	ds_read_b128 v[122:125], v108 offset:4096
	ds_read_b128 v[126:129], v109 offset:20480
	s_waitcnt lgkmcnt(0)
	v_mfma_f32_32x32x16_bf16 v[48:63], v[118:121], v[114:117], v[48:63]
	v_mfma_f32_32x32x16_bf16 v[32:47], v[126:129], v[114:117], v[32:47]
	v_mfma_f32_32x32x16_bf16 v[16:31], v[118:121], v[122:125], v[16:31]
	v_mfma_f32_32x32x16_bf16 v[0:15], v[126:129], v[122:125], v[0:15]
	ds_read_b128 v[114:117], v110
	ds_read_b128 v[118:121], v111 offset:16384
	ds_read_b128 v[122:125], v110 offset:4096
	ds_read_b128 v[126:129], v111 offset:20480
	s_waitcnt lgkmcnt(0)
	v_mfma_f32_32x32x16_bf16 v[48:63], v[118:121], v[114:117], v[48:63]
	v_mfma_f32_32x32x16_bf16 v[32:47], v[126:129], v[114:117], v[32:47]
	v_mfma_f32_32x32x16_bf16 v[16:31], v[118:121], v[122:125], v[16:31]
	v_mfma_f32_32x32x16_bf16 v[0:15], v[126:129], v[122:125], v[0:15]
	ds_read_b128 v[114:117], v112
	ds_read_b128 v[118:121], v113 offset:16384
	ds_read_b128 v[122:125], v112 offset:4096
	ds_read_b128 v[126:129], v113 offset:20480
	s_waitcnt vmcnt(0)
	s_waitcnt vmcnt(0) lgkmcnt(0)
	s_barrier
	v_mfma_f32_32x32x16_bf16 v[48:63], v[118:121], v[114:117], v[48:63]
	v_mfma_f32_32x32x16_bf16 v[32:47], v[126:129], v[114:117], v[32:47]
	global_load_lds_dwordx4 v64, s[98:99]
	s_mov_b32 m0, s15
	s_nop 0
	global_load_lds_dwordx4 v66, s[98:99]
	s_mov_b32 m0, s28
	v_mfma_f32_32x32x16_bf16 v[16:31], v[118:121], v[122:125], v[16:31]
	global_load_lds_dwordx4 v68, s[98:99]
	s_mov_b32 m0, s29
	s_nop 0
	global_load_lds_dwordx4 v70, s[98:99]
	s_mov_b32 m0, s34
	v_mfma_f32_32x32x16_bf16 v[0:15], v[126:129], v[122:125], v[0:15]
	global_load_lds_dwordx4 v64, s[100:101]
	s_mov_b32 m0, s35
	s_nop 0
	global_load_lds_dwordx4 v66, s[100:101]
	s_mov_b32 m0, s68
	s_nop 0
	global_load_lds_dwordx4 v68, s[100:101]
	s_mov_b32 m0, s69
	s_nop 0
	global_load_lds_dwordx4 v70, s[100:101]
	s_add_u32 s98, s98, 0x80
	s_addc_u32 s99, s99, 0
	s_add_u32 s100, s100, 0x80
	s_addc_u32 s101, s101, 0
	ds_read_b128 v[114:117], v106 offset:32768
	ds_read_b128 v[118:121], v107 offset:49152
	ds_read_b128 v[122:125], v106 offset:36864
	ds_read_b128 v[126:129], v107 offset:53248
	s_waitcnt lgkmcnt(0)
	v_mfma_f32_32x32x16_bf16 v[16:31], v[118:121], v[122:125], v[16:31]
	s_mov_b32 m0, s70
	v_mfma_f32_32x32x16_bf16 v[0:15], v[126:129], v[122:125], v[0:15]
	v_mfma_f32_32x32x16_bf16 v[32:47], v[126:129], v[114:117], v[32:47]
	v_mfma_f32_32x32x16_bf16 v[48:63], v[118:121], v[114:117], v[48:63]
	ds_read_b128 v[114:117], v108 offset:32768
	ds_read_b128 v[118:121], v109 offset:49152
	ds_read_b128 v[122:125], v108 offset:36864
	ds_read_b128 v[126:129], v109 offset:53248
	s_waitcnt lgkmcnt(0)
	v_mfma_f32_32x32x16_bf16 v[16:31], v[118:121], v[122:125], v[16:31]
	v_mfma_f32_32x32x16_bf16 v[0:15], v[126:129], v[122:125], v[0:15]
	v_mfma_f32_32x32x16_bf16 v[32:47], v[126:129], v[114:117], v[32:47]
	v_mfma_f32_32x32x16_bf16 v[48:63], v[118:121], v[114:117], v[48:63]
	ds_read_b128 v[114:117], v110 offset:32768
	ds_read_b128 v[118:121], v111 offset:49152
	ds_read_b128 v[122:125], v110 offset:36864
	ds_read_b128 v[126:129], v111 offset:53248
	s_waitcnt lgkmcnt(0)
	v_mfma_f32_32x32x16_bf16 v[16:31], v[118:121], v[122:125], v[16:31]
	v_mfma_f32_32x32x16_bf16 v[0:15], v[126:129], v[122:125], v[0:15]
	v_mfma_f32_32x32x16_bf16 v[32:47], v[126:129], v[114:117], v[32:47]
	v_mfma_f32_32x32x16_bf16 v[48:63], v[118:121], v[114:117], v[48:63]
	ds_read_b128 v[114:117], v112 offset:32768
	ds_read_b128 v[118:121], v113 offset:49152
	ds_read_b128 v[122:125], v112 offset:36864
	ds_read_b128 v[126:129], v113 offset:53248
	s_waitcnt vmcnt(0)
	s_waitcnt vmcnt(0) lgkmcnt(0)
	s_barrier
	global_load_lds_dwordx4 v64, s[98:99]
	s_mov_b32 m0, s71
	v_mfma_f32_32x32x16_bf16 v[16:31], v[118:121], v[122:125], v[16:31]
	global_load_lds_dwordx4 v66, s[98:99]
	s_mov_b32 m0, s72
	s_nop 0
	global_load_lds_dwordx4 v68, s[98:99]
	s_mov_b32 m0, s73
	v_mfma_f32_32x32x16_bf16 v[0:15], v[126:129], v[122:125], v[0:15]
	global_load_lds_dwordx4 v70, s[98:99]
	s_mov_b32 m0, s84
	s_nop 0
	global_load_lds_dwordx4 v64, s[100:101]
	s_mov_b32 m0, s85
	v_mfma_f32_32x32x16_bf16 v[32:47], v[126:129], v[114:117], v[32:47]
	global_load_lds_dwordx4 v66, s[100:101]
	s_mov_b32 m0, s86
	s_nop 0
	global_load_lds_dwordx4 v68, s[100:101]
	s_mov_b32 m0, s87
	v_mfma_f32_32x32x16_bf16 v[48:63], v[118:121], v[114:117], v[48:63]
	global_load_lds_dwordx4 v70, s[100:101]
	ds_read_b128 v[72:75], v106
	ds_read_b128 v[76:79], v107 offset:16384
	ds_read_b128 v[80:83], v106 offset:4096
	ds_read_b128 v[84:87], v107 offset:20480
	s_waitcnt lgkmcnt(0)
	v_mfma_f32_32x32x16_bf16 v[16:31], v[76:79], v[80:83], v[16:31]
	v_mfma_f32_32x32x16_bf16 v[0:15], v[84:87], v[80:83], v[0:15]
	v_mfma_f32_32x32x16_bf16 v[32:47], v[84:87], v[72:75], v[32:47]
	v_mfma_f32_32x32x16_bf16 v[48:63], v[76:79], v[72:75], v[48:63]
	ds_read_b128 v[72:75], v108
	ds_read_b128 v[76:79], v109 offset:16384
	ds_read_b128 v[80:83], v108 offset:4096
	ds_read_b128 v[84:87], v109 offset:20480
	s_waitcnt lgkmcnt(0)
	v_mfma_f32_32x32x16_bf16 v[16:31], v[76:79], v[80:83], v[16:31]
	v_mfma_f32_32x32x16_bf16 v[0:15], v[84:87], v[80:83], v[0:15]
	v_mfma_f32_32x32x16_bf16 v[32:47], v[84:87], v[72:75], v[32:47]
	v_mfma_f32_32x32x16_bf16 v[48:63], v[76:79], v[72:75], v[48:63]
	ds_read_b128 v[72:75], v110
	ds_read_b128 v[76:79], v111 offset:16384
	ds_read_b128 v[80:83], v110 offset:4096
	ds_read_b128 v[84:87], v111 offset:20480
	s_waitcnt lgkmcnt(0)
	v_mfma_f32_32x32x16_bf16 v[16:31], v[76:79], v[80:83], v[16:31]
	v_mfma_f32_32x32x16_bf16 v[0:15], v[84:87], v[80:83], v[0:15]
	v_mfma_f32_32x32x16_bf16 v[32:47], v[84:87], v[72:75], v[32:47]
	v_mfma_f32_32x32x16_bf16 v[48:63], v[76:79], v[72:75], v[48:63]
	ds_read_b128 v[72:75], v112
	ds_read_b128 v[76:79], v113 offset:16384
	ds_read_b128 v[80:83], v112 offset:4096
	ds_read_b128 v[84:87], v113 offset:20480
	s_waitcnt vmcnt(0)
	s_waitcnt vmcnt(0) lgkmcnt(0)
	s_barrier
	v_mfma_f32_32x32x16_bf16 v[16:31], v[76:79], v[80:83], v[16:31]
	v_mfma_f32_32x32x16_bf16 v[0:15], v[84:87], v[80:83], v[0:15]
	v_mfma_f32_32x32x16_bf16 v[32:47], v[84:87], v[72:75], v[32:47]
	v_mfma_f32_32x32x16_bf16 v[48:63], v[76:79], v[72:75], v[48:63]
	ds_read_b128 v[72:75], v113 offset:53248
	ds_read_b128 v[76:79], v112 offset:36864
	ds_read_b128 v[80:83], v113 offset:49152
	ds_read_b128 v[84:87], v112 offset:32768
	ds_read_b128 v[114:117], v111 offset:53248
	ds_read_b128 v[118:121], v110 offset:36864
	ds_read_b128 v[122:125], v111 offset:49152
	ds_read_b128 v[126:129], v110 offset:32768
	ds_read_b128 v[130:133], v109 offset:53248
	ds_read_b128 v[134:137], v108 offset:36864
	ds_read_b128 v[138:141], v109 offset:49152
	ds_read_b128 v[142:145], v108 offset:32768
	ds_read_b128 v[146:149], v107 offset:53248
	ds_read_b128 v[150:153], v106 offset:36864
	ds_read_b128 v[156:159], v107 offset:49152
	ds_read_b128 v[160:163], v106 offset:32768
	s_waitcnt vmcnt(0)
	s_waitcnt lgkmcnt(0)
	s_barrier
	v_mfma_f32_32x32x16_bf16 v[16:31], v[156:159], v[150:153], v[16:31]
	v_mfma_f32_32x32x16_bf16 v[0:15], v[146:149], v[150:153], v[0:15]
	v_mfma_f32_32x32x16_bf16 v[32:47], v[146:149], v[160:163], v[32:47]
	v_mfma_f32_32x32x16_bf16 v[48:63], v[156:159], v[160:163], v[48:63]
	v_mfma_f32_32x32x16_bf16 v[16:31], v[138:141], v[134:137], v[16:31]
	v_mfma_f32_32x32x16_bf16 v[0:15], v[130:133], v[134:137], v[0:15]
	v_mfma_f32_32x32x16_bf16 v[32:47], v[130:133], v[142:145], v[32:47]
	v_mfma_f32_32x32x16_bf16 v[48:63], v[138:141], v[142:145], v[48:63]
	v_mfma_f32_32x32x16_bf16 v[16:31], v[122:125], v[118:121], v[16:31]
	v_mfma_f32_32x32x16_bf16 v[0:15], v[114:117], v[118:121], v[0:15]
	v_mfma_f32_32x32x16_bf16 v[32:47], v[114:117], v[126:129], v[32:47]
	v_mfma_f32_32x32x16_bf16 v[48:63], v[122:125], v[126:129], v[48:63]
	v_mfma_f32_32x32x16_bf16 v[16:31], v[80:83], v[76:79], v[16:31]
	v_mfma_f32_32x32x16_bf16 v[0:15], v[72:75], v[76:79], v[0:15]
	v_add_u32_e32 v76, s94, v89
	v_ashrrev_i32_e32 v77, 31, v76
	v_mfma_f32_32x32x16_bf16 v[32:47], v[72:75], v[84:87], v[32:47]
	v_or_b32_e32 v72, s96, v90
	v_lshlrev_b64 v[74:75], 12, v[76:77]
	v_ashrrev_i32_e32 v73, 31, v72
	v_lshl_add_u64 v[78:79], s[52:53], 0, v[74:75]
	v_mfma_f32_32x32x16_bf16 v[48:63], v[80:83], v[84:87], v[48:63]
	v_lshlrev_b64 v[82:83], 2, v[72:73]
	v_lshl_add_u64 v[78:79], v[78:79], 0, v[82:83]
	v_lshl_add_u64 v[80:81], s[38:39], 0, v[74:75]
	v_lshl_add_u64 v[228:229], v[80:81], 0, v[82:83]
	v_or_b32_e32 v234, 32, v76
	v_ashrrev_i32_e32 v235, 31, v234
	v_lshlrev_b64 v[234:235], 12, v[234:235]
	v_lshl_add_u64 v[230:231], s[52:53], 0, v[234:235]
	v_lshl_add_u64 v[230:231], v[230:231], 0, v[82:83]
	v_lshl_add_u64 v[232:233], s[38:39], 0, v[234:235]
	v_lshl_add_u64 v[232:233], v[232:233], 0, v[82:83]
	global_load_dwordx4 v[164:167], v[78:79], off
	global_load_dwordx4 v[168:171], v[78:79], off offset:32
	global_load_dwordx4 v[172:175], v[78:79], off offset:64
	global_load_dwordx4 v[176:179], v[78:79], off offset:96
	global_load_dwordx4 v[180:183], v[78:79], off offset:128
	global_load_dwordx4 v[184:187], v[78:79], off offset:160
	global_load_dwordx4 v[188:191], v[78:79], off offset:192
	global_load_dwordx4 v[192:195], v[78:79], off offset:224
	global_load_dwordx4 v[196:199], v[230:231], off
	global_load_dwordx4 v[200:203], v[230:231], off offset:32
	global_load_dwordx4 v[204:207], v[230:231], off offset:64
	global_load_dwordx4 v[208:211], v[230:231], off offset:96
	global_load_dwordx4 v[212:215], v[230:231], off offset:128
	global_load_dwordx4 v[216:219], v[230:231], off offset:160
	global_load_dwordx4 v[220:223], v[230:231], off offset:192
	global_load_dwordx4 v[224:227], v[230:231], off offset:224
	s_waitcnt vmcnt(15)
	v_pk_fma_f32 v[166:167], v[166:167], s[92:93], v[50:51] op_sel_hi:[1,0,1]
	v_pk_fma_f32 v[164:165], v[164:165], s[92:93], v[48:49] op_sel_hi:[1,0,1]
	global_store_dwordx4 v[228:229], v[164:167], off
	s_waitcnt vmcnt(15)
	v_pk_fma_f32 v[168:169], v[168:169], s[92:93], v[52:53] op_sel_hi:[1,0,1]
	v_pk_fma_f32 v[170:171], v[170:171], s[92:93], v[54:55] op_sel_hi:[1,0,1]
	global_store_dwordx4 v[228:229], v[168:171], off offset:32
	s_waitcnt vmcnt(15)
	v_pk_fma_f32 v[172:173], v[172:173], s[92:93], v[56:57] op_sel_hi:[1,0,1]
	v_pk_fma_f32 v[174:175], v[174:175], s[92:93], v[58:59] op_sel_hi:[1,0,1]
	global_store_dwordx4 v[228:229], v[172:175], off offset:64
	s_waitcnt vmcnt(15)
	v_pk_fma_f32 v[176:177], v[176:177], s[92:93], v[60:61] op_sel_hi:[1,0,1]
	v_pk_fma_f32 v[178:179], v[178:179], s[92:93], v[62:63] op_sel_hi:[1,0,1]
	global_store_dwordx4 v[228:229], v[176:179], off offset:96
	s_waitcnt vmcnt(15)
	v_pk_fma_f32 v[182:183], v[182:183], s[92:93], v[34:35] op_sel_hi:[1,0,1]
	v_pk_fma_f32 v[180:181], v[180:181], s[92:93], v[32:33] op_sel_hi:[1,0,1]
	global_store_dwordx4 v[228:229], v[180:183], off offset:128
	s_waitcnt vmcnt(15)
	v_pk_fma_f32 v[184:185], v[184:185], s[92:93], v[36:37] op_sel_hi:[1,0,1]
	v_pk_fma_f32 v[186:187], v[186:187], s[92:93], v[38:39] op_sel_hi:[1,0,1]
	global_store_dwordx4 v[228:229], v[184:187], off offset:160
	s_waitcnt vmcnt(15)
	v_pk_fma_f32 v[188:189], v[188:189], s[92:93], v[40:41] op_sel_hi:[1,0,1]
	v_pk_fma_f32 v[190:191], v[190:191], s[92:93], v[42:43] op_sel_hi:[1,0,1]
	global_store_dwordx4 v[228:229], v[188:191], off offset:192
	s_waitcnt vmcnt(15)
	v_pk_fma_f32 v[192:193], v[192:193], s[92:93], v[44:45] op_sel_hi:[1,0,1]
	v_pk_fma_f32 v[194:195], v[194:195], s[92:93], v[46:47] op_sel_hi:[1,0,1]
	global_store_dwordx4 v[228:229], v[192:195], off offset:224
	s_waitcnt vmcnt(15)
	v_pk_fma_f32 v[198:199], v[198:199], s[92:93], v[18:19] op_sel_hi:[1,0,1]
	v_pk_fma_f32 v[196:197], v[196:197], s[92:93], v[16:17] op_sel_hi:[1,0,1]
	global_store_dwordx4 v[232:233], v[196:199], off
	s_waitcnt vmcnt(15)
	v_pk_fma_f32 v[200:201], v[200:201], s[92:93], v[20:21] op_sel_hi:[1,0,1]
	v_pk_fma_f32 v[202:203], v[202:203], s[92:93], v[22:23] op_sel_hi:[1,0,1]
	global_store_dwordx4 v[232:233], v[200:203], off offset:32
	s_waitcnt vmcnt(15)
	v_pk_fma_f32 v[204:205], v[204:205], s[92:93], v[24:25] op_sel_hi:[1,0,1]
	v_pk_fma_f32 v[206:207], v[206:207], s[92:93], v[26:27] op_sel_hi:[1,0,1]
	global_store_dwordx4 v[232:233], v[204:207], off offset:64
	s_waitcnt vmcnt(15)
	v_pk_fma_f32 v[208:209], v[208:209], s[92:93], v[28:29] op_sel_hi:[1,0,1]
	v_pk_fma_f32 v[210:211], v[210:211], s[92:93], v[30:31] op_sel_hi:[1,0,1]
	global_store_dwordx4 v[232:233], v[208:211], off offset:96
	s_waitcnt vmcnt(15)
	v_pk_fma_f32 v[214:215], v[214:215], s[92:93], v[2:3] op_sel_hi:[1,0,1]
	v_pk_fma_f32 v[212:213], v[212:213], s[92:93], v[0:1] op_sel_hi:[1,0,1]
	global_store_dwordx4 v[232:233], v[212:215], off offset:128
	s_waitcnt vmcnt(15)
	v_pk_fma_f32 v[216:217], v[216:217], s[92:93], v[4:5] op_sel_hi:[1,0,1]
	v_pk_fma_f32 v[218:219], v[218:219], s[92:93], v[6:7] op_sel_hi:[1,0,1]
	global_store_dwordx4 v[232:233], v[216:219], off offset:160
	s_waitcnt vmcnt(15)
	v_pk_fma_f32 v[220:221], v[220:221], s[92:93], v[8:9] op_sel_hi:[1,0,1]
	v_pk_fma_f32 v[222:223], v[222:223], s[92:93], v[10:11] op_sel_hi:[1,0,1]
	global_store_dwordx4 v[232:233], v[220:223], off offset:192
	s_waitcnt vmcnt(15)
	v_pk_fma_f32 v[224:225], v[224:225], s[92:93], v[12:13] op_sel_hi:[1,0,1]
	v_pk_fma_f32 v[226:227], v[226:227], s[92:93], v[14:15] op_sel_hi:[1,0,1]
	global_store_dwordx4 v[232:233], v[224:227], off offset:224
	s_cmpk_lt_i32 s14, 0x400
	s_cbranch_scc0 .LBB0_255

.LBB0_561:
	s_lshl_b32 s80, s28, 7
	v_readlane_b32 s44, v245, 59
	s_ashr_i32 s81, s80, 31
	v_readlane_b32 s45, v245, 60
	s_lshl_b32 s82, s29, 7
	s_lshl_b64 s[28:29], s[80:81], 11
	v_readlane_b32 s46, v245, 61
	v_readlane_b32 s47, v245, 62
	v_readlane_b32 s48, v245, 63
	v_readlane_b32 s49, v244, 0
	s_mov_b64 s[36:37], s[44:45]
	v_readlane_b32 s52, v244, 3
	v_readlane_b32 s53, v244, 4
	v_readlane_b32 s54, v244, 5
	v_readlane_b32 s55, v244, 6
	v_readlane_b32 s56, v244, 7
	v_readlane_b32 s57, v244, 8
	v_readlane_b32 s58, v244, 9
	v_readlane_b32 s59, v244, 10
	s_add_u32 s34, s36, s28
	s_addc_u32 s35, s37, s29
	s_ashr_i32 s83, s82, 31
	v_readlane_b32 s52, v245, 37
	s_lshl_b64 s[28:29], s[82:83], 11
	v_readlane_b32 s56, v245, 41
	v_readlane_b32 s57, v245, 42
	s_add_u32 s70, s56, s28
	s_addc_u32 s71, s57, s29
	v_readfirstlane_b32 s29, v88
	v_mov_b32_e32 v2, s71
	v_mov_b32_e32 v3, s35
	v_mov_b32_e32 v4, s70
	v_mov_b32_e32 v5, s34
	s_add_u32 s98, s34, 0x80
	s_addc_u32 s99, s35, 0
	v_lshl_add_u64 v[72:73], s[34:35], 0, v[64:65]
	s_mov_b32 m0, s29
	v_cndmask_b32_e64 v1, v2, v3, s[4:5]
	v_cndmask_b32_e64 v0, v4, v5, s[4:5]
	v_readfirstlane_b32 s84, v91
	global_load_lds_dwordx4 v[72:73], off
	v_lshl_add_u64 v[74:75], v[0:1], 0, v[66:67]
	s_mov_b32 m0, s84
	v_cndmask_b32_e64 v1, v2, v3, s[6:7]
	v_cndmask_b32_e64 v0, v4, v5, s[6:7]
	v_readfirstlane_b32 s85, v92
	global_load_lds_dwordx4 v[74:75], off
	v_lshl_add_u64 v[76:77], v[0:1], 0, v[68:69]
	s_mov_b32 m0, s85
	v_cndmask_b32_e64 v1, v2, v3, s[8:9]
	v_cndmask_b32_e64 v0, v4, v5, s[8:9]
	v_readfirstlane_b32 s86, v93
	global_load_lds_dwordx4 v[76:77], off
	v_lshl_add_u64 v[78:79], v[0:1], 0, v[70:71]
	s_mov_b32 m0, s86
	v_readfirstlane_b32 s87, v94
	global_load_lds_dwordx4 v[78:79], off
	s_add_u32 s100, s70, 0x80
	s_addc_u32 s101, s71, 0
	v_lshl_add_u64 v[80:81], s[70:71], 0, v[64:65]
	s_mov_b32 m0, s87
	v_readfirstlane_b32 s89, v95
	global_load_lds_dwordx4 v[80:81], off
	v_lshl_add_u64 v[82:83], s[70:71], 0, v[66:67]
	s_mov_b32 m0, s89
	v_readfirstlane_b32 s90, v96
	global_load_lds_dwordx4 v[82:83], off
	v_lshl_add_u64 v[84:85], s[70:71], 0, v[68:69]
	s_mov_b32 m0, s90
	v_readfirstlane_b32 s91, v97
	global_load_lds_dwordx4 v[84:85], off
	v_lshl_add_u64 v[86:87], s[70:71], 0, v[70:71]
	s_mov_b32 m0, s91
	v_readfirstlane_b32 s70, v98
	global_load_lds_dwordx4 v[86:87], off
	s_mov_b32 m0, s70
	v_readfirstlane_b32 s71, v99
	s_waitcnt vmcnt(0)
	s_waitcnt vmcnt(0) lgkmcnt(0)
	s_barrier
	global_load_lds_dwordx4 v64, s[98:99]
	s_mov_b32 m0, s71
	v_readfirstlane_b32 s72, v100
	global_load_lds_dwordx4 v66, s[98:99]
	s_mov_b32 m0, s72
	v_readfirstlane_b32 s73, v101
	global_load_lds_dwordx4 v68, s[98:99]
	s_mov_b32 m0, s73
	v_readfirstlane_b32 s81, v102
	global_load_lds_dwordx4 v70, s[98:99]
	s_mov_b32 m0, s81
	v_readfirstlane_b32 s83, v103
	global_load_lds_dwordx4 v64, s[100:101]
	s_mov_b32 m0, s83
	v_readfirstlane_b32 s88, v104
	global_load_lds_dwordx4 v66, s[100:101]
	s_mov_b32 m0, s88
	v_readfirstlane_b32 s28, v105
	global_load_lds_dwordx4 v68, s[100:101]
	s_mov_b32 m0, s28
	v_readfirstlane_b32 s34, v92
	global_load_lds_dwordx4 v70, s[100:101]
	s_add_u32 s98, s98, 0x80
	s_addc_u32 s99, s99, 0
	s_add_u32 s100, s100, 0x80
	s_addc_u32 s101, s101, 0
	ds_read_b128 v[0:3], v106
	ds_read_b128 v[4:7], v107 offset:16384
	ds_read_b128 v[8:11], v106 offset:4096
	ds_read_b128 v[12:15], v107 offset:20480
	s_waitcnt lgkmcnt(0)
	v_mfma_f32_32x32x16_bf16 v[48:63], v[4:7], v[0:3], 0
	ds_read_b128 v[114:117], v108
	ds_read_b128 v[118:121], v109 offset:16384
	ds_read_b128 v[122:125], v108 offset:4096
	ds_read_b128 v[126:129], v109 offset:20480
	s_mov_b32 m0, s29
	v_readfirstlane_b32 s35, v93
	s_mov_b64 s[40:41], s[48:49]
	s_mov_b64 s[38:39], s[46:47]
	v_readlane_b32 s50, v244, 1
	v_readlane_b32 s51, v244, 2
	v_mfma_f32_32x32x16_bf16 v[32:47], v[12:15], v[0:3], 0
	v_readlane_b32 s53, v245, 38
	v_readlane_b32 s54, v245, 39
	v_readlane_b32 s55, v245, 40
	v_readlane_b32 s58, v245, 43
	v_readlane_b32 s59, v245, 44
	v_readlane_b32 s60, v245, 45
	v_readlane_b32 s61, v245, 46
	v_mfma_f32_32x32x16_bf16 v[16:31], v[4:7], v[8:11], 0
	v_readlane_b32 s62, v245, 47
	v_readlane_b32 s63, v245, 48
	v_readlane_b32 s64, v245, 49
	v_readlane_b32 s65, v245, 50
	v_readlane_b32 s66, v245, 51
	v_readlane_b32 s67, v245, 52
	v_mfma_f32_32x32x16_bf16 v[0:15], v[12:15], v[8:11], 0
	s_waitcnt lgkmcnt(0)
	v_mfma_f32_32x32x16_bf16 v[48:63], v[118:121], v[114:117], v[48:63]
	v_mfma_f32_32x32x16_bf16 v[32:47], v[126:129], v[114:117], v[32:47]
	v_mfma_f32_32x32x16_bf16 v[16:31], v[118:121], v[122:125], v[16:31]
	v_mfma_f32_32x32x16_bf16 v[0:15], v[126:129], v[122:125], v[0:15]
	ds_read_b128 v[114:117], v110
	ds_read_b128 v[118:121], v111 offset:16384
	ds_read_b128 v[122:125], v110 offset:4096
	ds_read_b128 v[126:129], v111 offset:20480
	s_waitcnt lgkmcnt(0)
	v_mfma_f32_32x32x16_bf16 v[48:63], v[118:121], v[114:117], v[48:63]
	v_mfma_f32_32x32x16_bf16 v[32:47], v[126:129], v[114:117], v[32:47]
	v_mfma_f32_32x32x16_bf16 v[16:31], v[118:121], v[122:125], v[16:31]
	v_mfma_f32_32x32x16_bf16 v[0:15], v[126:129], v[122:125], v[0:15]
	ds_read_b128 v[114:117], v112
	ds_read_b128 v[118:121], v113 offset:16384
	ds_read_b128 v[122:125], v112 offset:4096
	ds_read_b128 v[126:129], v113 offset:20480
	s_waitcnt vmcnt(0)
	s_waitcnt vmcnt(0) lgkmcnt(0)
	s_barrier
	v_mfma_f32_32x32x16_bf16 v[48:63], v[118:121], v[114:117], v[48:63]
	v_mfma_f32_32x32x16_bf16 v[32:47], v[126:129], v[114:117], v[32:47]
	global_load_lds_dwordx4 v64, s[98:99]
	s_mov_b32 m0, s84
	s_nop 0
	global_load_lds_dwordx4 v66, s[98:99]
	s_mov_b32 m0, s85
	v_mfma_f32_32x32x16_bf16 v[16:31], v[118:121], v[122:125], v[16:31]
	global_load_lds_dwordx4 v68, s[98:99]
	s_mov_b32 m0, s86
	s_nop 0
	global_load_lds_dwordx4 v70, s[98:99]
	s_mov_b32 m0, s87
	v_mfma_f32_32x32x16_bf16 v[0:15], v[126:129], v[122:125], v[0:15]
	global_load_lds_dwordx4 v64, s[100:101]
	s_mov_b32 m0, s89
	s_nop 0
	global_load_lds_dwordx4 v66, s[100:101]
	s_mov_b32 m0, s90
	s_nop 0
	global_load_lds_dwordx4 v68, s[100:101]
	s_mov_b32 m0, s91
	s_nop 0
	global_load_lds_dwordx4 v70, s[100:101]
	s_add_u32 s98, s98, 0x80
	s_addc_u32 s99, s99, 0
	s_add_u32 s100, s100, 0x80
	s_addc_u32 s101, s101, 0
	ds_read_b128 v[114:117], v106 offset:32768
	ds_read_b128 v[118:121], v107 offset:49152
	ds_read_b128 v[122:125], v106 offset:36864
	ds_read_b128 v[126:129], v107 offset:53248
	s_waitcnt lgkmcnt(0)
	v_mfma_f32_32x32x16_bf16 v[48:63], v[118:121], v[114:117], v[48:63]
	s_mov_b32 m0, s70
	v_mfma_f32_32x32x16_bf16 v[32:47], v[126:129], v[114:117], v[32:47]
	v_mfma_f32_32x32x16_bf16 v[16:31], v[118:121], v[122:125], v[16:31]
	v_mfma_f32_32x32x16_bf16 v[0:15], v[126:129], v[122:125], v[0:15]
	ds_read_b128 v[114:117], v108 offset:32768
	ds_read_b128 v[118:121], v109 offset:49152
	ds_read_b128 v[122:125], v108 offset:36864
	ds_read_b128 v[126:129], v109 offset:53248
	s_waitcnt lgkmcnt(0)
	v_mfma_f32_32x32x16_bf16 v[48:63], v[118:121], v[114:117], v[48:63]
	v_mfma_f32_32x32x16_bf16 v[32:47], v[126:129], v[114:117], v[32:47]
	v_mfma_f32_32x32x16_bf16 v[16:31], v[118:121], v[122:125], v[16:31]
	v_mfma_f32_32x32x16_bf16 v[0:15], v[126:129], v[122:125], v[0:15]
	ds_read_b128 v[114:117], v110 offset:32768
	ds_read_b128 v[118:121], v111 offset:49152
	ds_read_b128 v[122:125], v110 offset:36864
	ds_read_b128 v[126:129], v111 offset:53248
	s_waitcnt lgkmcnt(0)
	v_mfma_f32_32x32x16_bf16 v[48:63], v[118:121], v[114:117], v[48:63]
	v_mfma_f32_32x32x16_bf16 v[32:47], v[126:129], v[114:117], v[32:47]
	v_mfma_f32_32x32x16_bf16 v[16:31], v[118:121], v[122:125], v[16:31]
	v_mfma_f32_32x32x16_bf16 v[0:15], v[126:129], v[122:125], v[0:15]
	ds_read_b128 v[114:117], v112 offset:32768
	ds_read_b128 v[118:121], v113 offset:49152
	ds_read_b128 v[122:125], v112 offset:36864
	ds_read_b128 v[126:129], v113 offset:53248
	s_waitcnt vmcnt(0)
	s_waitcnt vmcnt(0) lgkmcnt(0)
	s_barrier
	v_mfma_f32_32x32x16_bf16 v[48:63], v[118:121], v[114:117], v[48:63]
	v_mfma_f32_32x32x16_bf16 v[32:47], v[126:129], v[114:117], v[32:47]
	global_load_lds_dwordx4 v64, s[98:99]
	s_mov_b32 m0, s71
	s_nop 0
	global_load_lds_dwordx4 v66, s[98:99]
	s_mov_b32 m0, s72
	v_mfma_f32_32x32x16_bf16 v[16:31], v[118:121], v[122:125], v[16:31]
	global_load_lds_dwordx4 v68, s[98:99]
	s_mov_b32 m0, s73
	s_nop 0
	global_load_lds_dwordx4 v70, s[98:99]
	s_mov_b32 m0, s81
	v_mfma_f32_32x32x16_bf16 v[0:15], v[126:129], v[122:125], v[0:15]
	global_load_lds_dwordx4 v64, s[100:101]
	s_mov_b32 m0, s83
	s_nop 0
	global_load_lds_dwordx4 v66, s[100:101]
	s_mov_b32 m0, s88
	s_nop 0
	global_load_lds_dwordx4 v68, s[100:101]
	s_mov_b32 m0, s28
	s_nop 0
	global_load_lds_dwordx4 v70, s[100:101]
	s_add_u32 s98, s98, 0x80
	s_addc_u32 s99, s99, 0
	s_add_u32 s100, s100, 0x80
	s_addc_u32 s101, s101, 0
	ds_read_b128 v[114:117], v106
	ds_read_b128 v[118:121], v107 offset:16384
	ds_read_b128 v[122:125], v106 offset:4096
	ds_read_b128 v[126:129], v107 offset:20480
	s_waitcnt lgkmcnt(0)
	v_mfma_f32_32x32x16_bf16 v[48:63], v[118:121], v[114:117], v[48:63]
	s_mov_b32 m0, s29
	v_mfma_f32_32x32x16_bf16 v[32:47], v[126:129], v[114:117], v[32:47]
	v_mfma_f32_32x32x16_bf16 v[16:31], v[118:121], v[122:125], v[16:31]
	v_mfma_f32_32x32x16_bf16 v[0:15], v[126:129], v[122:125], v[0:15]
	ds_read_b128 v[114:117], v108
	ds_read_b128 v[118:121], v109 offset:16384
	ds_read_b128 v[122:125], v108 offset:4096
	ds_read_b128 v[126:129], v109 offset:20480
	s_waitcnt lgkmcnt(0)
	v_mfma_f32_32x32x16_bf16 v[48:63], v[118:121], v[114:117], v[48:63]
	v_mfma_f32_32x32x16_bf16 v[32:47], v[126:129], v[114:117], v[32:47]
	v_mfma_f32_32x32x16_bf16 v[16:31], v[118:121], v[122:125], v[16:31]
	v_mfma_f32_32x32x16_bf16 v[0:15], v[126:129], v[122:125], v[0:15]
	ds_read_b128 v[114:117], v110
	ds_read_b128 v[118:121], v111 offset:16384
	ds_read_b128 v[122:125], v110 offset:4096
	ds_read_b128 v[126:129], v111 offset:20480
	s_waitcnt lgkmcnt(0)
	v_mfma_f32_32x32x16_bf16 v[48:63], v[118:121], v[114:117], v[48:63]
	v_mfma_f32_32x32x16_bf16 v[32:47], v[126:129], v[114:117], v[32:47]
	v_mfma_f32_32x32x16_bf16 v[16:31], v[118:121], v[122:125], v[16:31]
	v_mfma_f32_32x32x16_bf16 v[0:15], v[126:129], v[122:125], v[0:15]
	ds_read_b128 v[114:117], v112
	ds_read_b128 v[118:121], v113 offset:16384
	ds_read_b128 v[122:125], v112 offset:4096
	ds_read_b128 v[126:129], v113 offset:20480
	s_waitcnt vmcnt(0)
	s_waitcnt vmcnt(0) lgkmcnt(0)
	s_barrier
	v_mfma_f32_32x32x16_bf16 v[48:63], v[118:121], v[114:117], v[48:63]
	v_mfma_f32_32x32x16_bf16 v[32:47], v[126:129], v[114:117], v[32:47]
	global_load_lds_dwordx4 v64, s[98:99]
	s_mov_b32 m0, s84
	s_nop 0
	global_load_lds_dwordx4 v66, s[98:99]
	s_mov_b32 m0, s85
	v_mfma_f32_32x32x16_bf16 v[16:31], v[118:121], v[122:125], v[16:31]
	global_load_lds_dwordx4 v68, s[98:99]
	s_mov_b32 m0, s86
	s_nop 0
	global_load_lds_dwordx4 v70, s[98:99]
	s_mov_b32 m0, s87
	v_mfma_f32_32x32x16_bf16 v[0:15], v[126:129], v[122:125], v[0:15]
	global_load_lds_dwordx4 v64, s[100:101]
	s_mov_b32 m0, s89
	s_nop 0
	global_load_lds_dwordx4 v66, s[100:101]
	s_mov_b32 m0, s90
	s_nop 0
	global_load_lds_dwordx4 v68, s[100:101]
	s_mov_b32 m0, s91
	s_nop 0
	global_load_lds_dwordx4 v70, s[100:101]
	s_add_u32 s98, s98, 0x80
	s_addc_u32 s99, s99, 0
	s_add_u32 s100, s100, 0x80
	s_addc_u32 s101, s101, 0
	ds_read_b128 v[114:117], v106 offset:32768
	ds_read_b128 v[118:121], v107 offset:49152
	ds_read_b128 v[122:125], v106 offset:36864
	ds_read_b128 v[126:129], v107 offset:53248
	s_waitcnt lgkmcnt(0)
	v_mfma_f32_32x32x16_bf16 v[48:63], v[118:121], v[114:117], v[48:63]
	s_mov_b32 m0, s70
	v_mfma_f32_32x32x16_bf16 v[32:47], v[126:129], v[114:117], v[32:47]
	v_mfma_f32_32x32x16_bf16 v[16:31], v[118:121], v[122:125], v[16:31]
	v_mfma_f32_32x32x16_bf16 v[0:15], v[126:129], v[122:125], v[0:15]
	ds_read_b128 v[114:117], v108 offset:32768
	ds_read_b128 v[118:121], v109 offset:49152
	ds_read_b128 v[122:125], v108 offset:36864
	ds_read_b128 v[126:129], v109 offset:53248
	s_waitcnt lgkmcnt(0)
	v_mfma_f32_32x32x16_bf16 v[48:63], v[118:121], v[114:117], v[48:63]
	v_mfma_f32_32x32x16_bf16 v[32:47], v[126:129], v[114:117], v[32:47]
	v_mfma_f32_32x32x16_bf16 v[16:31], v[118:121], v[122:125], v[16:31]
	v_mfma_f32_32x32x16_bf16 v[0:15], v[126:129], v[122:125], v[0:15]
	ds_read_b128 v[114:117], v110 offset:32768
	ds_read_b128 v[118:121], v111 offset:49152
	ds_read_b128 v[122:125], v110 offset:36864
	ds_read_b128 v[126:129], v111 offset:53248
	s_waitcnt lgkmcnt(0)
	v_mfma_f32_32x32x16_bf16 v[48:63], v[118:121], v[114:117], v[48:63]
	v_mfma_f32_32x32x16_bf16 v[32:47], v[126:129], v[114:117], v[32:47]
	v_mfma_f32_32x32x16_bf16 v[16:31], v[118:121], v[122:125], v[16:31]
	v_mfma_f32_32x32x16_bf16 v[0:15], v[126:129], v[122:125], v[0:15]
	ds_read_b128 v[114:117], v112 offset:32768
	ds_read_b128 v[118:121], v113 offset:49152
	ds_read_b128 v[122:125], v112 offset:36864
	ds_read_b128 v[126:129], v113 offset:53248
	s_waitcnt vmcnt(0)
	s_waitcnt vmcnt(0) lgkmcnt(0)
	s_barrier
	v_mfma_f32_32x32x16_bf16 v[48:63], v[118:121], v[114:117], v[48:63]
	v_mfma_f32_32x32x16_bf16 v[32:47], v[126:129], v[114:117], v[32:47]
	global_load_lds_dwordx4 v64, s[98:99]
	s_mov_b32 m0, s71
	s_nop 0
	global_load_lds_dwordx4 v66, s[98:99]
	s_mov_b32 m0, s72
	v_mfma_f32_32x32x16_bf16 v[16:31], v[118:121], v[122:125], v[16:31]
	global_load_lds_dwordx4 v68, s[98:99]
	s_mov_b32 m0, s73
	s_nop 0
	global_load_lds_dwordx4 v70, s[98:99]
	s_mov_b32 m0, s81
	v_mfma_f32_32x32x16_bf16 v[0:15], v[126:129], v[122:125], v[0:15]
	global_load_lds_dwordx4 v64, s[100:101]
	s_mov_b32 m0, s83
	s_nop 0
	global_load_lds_dwordx4 v66, s[100:101]
	s_mov_b32 m0, s88
	s_nop 0
	global_load_lds_dwordx4 v68, s[100:101]
	s_mov_b32 m0, s28
	s_nop 0
	global_load_lds_dwordx4 v70, s[100:101]
	s_add_u32 s98, s98, 0x80
	s_addc_u32 s99, s99, 0
	s_add_u32 s100, s100, 0x80
	s_addc_u32 s101, s101, 0
	ds_read_b128 v[114:117], v106
	ds_read_b128 v[118:121], v107 offset:16384
	ds_read_b128 v[122:125], v106 offset:4096
	ds_read_b128 v[126:129], v107 offset:20480
	s_waitcnt lgkmcnt(0)
	v_mfma_f32_32x32x16_bf16 v[48:63], v[118:121], v[114:117], v[48:63]
	s_mov_b32 m0, s29
	v_mfma_f32_32x32x16_bf16 v[32:47], v[126:129], v[114:117], v[32:47]
	v_mfma_f32_32x32x16_bf16 v[16:31], v[118:121], v[122:125], v[16:31]
	v_mfma_f32_32x32x16_bf16 v[0:15], v[126:129], v[122:125], v[0:15]
	ds_read_b128 v[114:117], v108
	ds_read_b128 v[118:121], v109 offset:16384
	ds_read_b128 v[122:125], v108 offset:4096
	ds_read_b128 v[126:129], v109 offset:20480
	s_waitcnt lgkmcnt(0)
	v_mfma_f32_32x32x16_bf16 v[48:63], v[118:121], v[114:117], v[48:63]
	v_mfma_f32_32x32x16_bf16 v[32:47], v[126:129], v[114:117], v[32:47]
	v_mfma_f32_32x32x16_bf16 v[16:31], v[118:121], v[122:125], v[16:31]
	v_mfma_f32_32x32x16_bf16 v[0:15], v[126:129], v[122:125], v[0:15]
	ds_read_b128 v[114:117], v110
	ds_read_b128 v[118:121], v111 offset:16384
	ds_read_b128 v[122:125], v110 offset:4096
	ds_read_b128 v[126:129], v111 offset:20480
	s_waitcnt lgkmcnt(0)
	v_mfma_f32_32x32x16_bf16 v[48:63], v[118:121], v[114:117], v[48:63]
	v_mfma_f32_32x32x16_bf16 v[32:47], v[126:129], v[114:117], v[32:47]
	v_mfma_f32_32x32x16_bf16 v[16:31], v[118:121], v[122:125], v[16:31]
	v_mfma_f32_32x32x16_bf16 v[0:15], v[126:129], v[122:125], v[0:15]
	ds_read_b128 v[114:117], v112
	ds_read_b128 v[118:121], v113 offset:16384
	ds_read_b128 v[122:125], v112 offset:4096
	ds_read_b128 v[126:129], v113 offset:20480
	s_waitcnt vmcnt(0)
	s_waitcnt vmcnt(0) lgkmcnt(0)
	s_barrier
	v_mfma_f32_32x32x16_bf16 v[48:63], v[118:121], v[114:117], v[48:63]
	v_mfma_f32_32x32x16_bf16 v[32:47], v[126:129], v[114:117], v[32:47]
	global_load_lds_dwordx4 v64, s[98:99]
	s_mov_b32 m0, s84
	s_nop 0
	global_load_lds_dwordx4 v66, s[98:99]
	s_mov_b32 m0, s85
	v_mfma_f32_32x32x16_bf16 v[16:31], v[118:121], v[122:125], v[16:31]
	global_load_lds_dwordx4 v68, s[98:99]
	s_mov_b32 m0, s86
	s_nop 0
	global_load_lds_dwordx4 v70, s[98:99]
	s_mov_b32 m0, s87
	v_mfma_f32_32x32x16_bf16 v[0:15], v[126:129], v[122:125], v[0:15]
	global_load_lds_dwordx4 v64, s[100:101]
	s_mov_b32 m0, s89
	s_nop 0
	global_load_lds_dwordx4 v66, s[100:101]
	s_mov_b32 m0, s90
	s_nop 0
	global_load_lds_dwordx4 v68, s[100:101]
	s_mov_b32 m0, s91
	s_nop 0
	global_load_lds_dwordx4 v70, s[100:101]
	s_add_u32 s98, s98, 0x80
	s_addc_u32 s99, s99, 0
	s_add_u32 s100, s100, 0x80
	s_addc_u32 s101, s101, 0
	ds_read_b128 v[114:117], v106 offset:32768
	ds_read_b128 v[118:121], v107 offset:49152
	ds_read_b128 v[122:125], v106 offset:36864
	ds_read_b128 v[126:129], v107 offset:53248
	s_waitcnt lgkmcnt(0)
	v_mfma_f32_32x32x16_bf16 v[48:63], v[118:121], v[114:117], v[48:63]
	s_mov_b32 m0, s70
	v_mfma_f32_32x32x16_bf16 v[32:47], v[126:129], v[114:117], v[32:47]
	v_mfma_f32_32x32x16_bf16 v[16:31], v[118:121], v[122:125], v[16:31]
	v_mfma_f32_32x32x16_bf16 v[0:15], v[126:129], v[122:125], v[0:15]
	ds_read_b128 v[114:117], v108 offset:32768
	ds_read_b128 v[118:121], v109 offset:49152
	ds_read_b128 v[122:125], v108 offset:36864
	ds_read_b128 v[126:129], v109 offset:53248
	s_waitcnt lgkmcnt(0)
	v_mfma_f32_32x32x16_bf16 v[48:63], v[118:121], v[114:117], v[48:63]
	v_mfma_f32_32x32x16_bf16 v[32:47], v[126:129], v[114:117], v[32:47]
	v_mfma_f32_32x32x16_bf16 v[16:31], v[118:121], v[122:125], v[16:31]
	v_mfma_f32_32x32x16_bf16 v[0:15], v[126:129], v[122:125], v[0:15]
	ds_read_b128 v[114:117], v110 offset:32768
	ds_read_b128 v[118:121], v111 offset:49152
	ds_read_b128 v[122:125], v110 offset:36864
	ds_read_b128 v[126:129], v111 offset:53248
	s_waitcnt lgkmcnt(0)
	v_mfma_f32_32x32x16_bf16 v[48:63], v[118:121], v[114:117], v[48:63]
	v_mfma_f32_32x32x16_bf16 v[32:47], v[126:129], v[114:117], v[32:47]
	v_mfma_f32_32x32x16_bf16 v[16:31], v[118:121], v[122:125], v[16:31]
	v_mfma_f32_32x32x16_bf16 v[0:15], v[126:129], v[122:125], v[0:15]
	ds_read_b128 v[114:117], v112 offset:32768
	ds_read_b128 v[118:121], v113 offset:49152
	ds_read_b128 v[122:125], v112 offset:36864
	ds_read_b128 v[126:129], v113 offset:53248
	s_waitcnt vmcnt(0)
	s_waitcnt vmcnt(0) lgkmcnt(0)
	s_barrier
	v_mfma_f32_32x32x16_bf16 v[48:63], v[118:121], v[114:117], v[48:63]
	v_mfma_f32_32x32x16_bf16 v[32:47], v[126:129], v[114:117], v[32:47]
	global_load_lds_dwordx4 v64, s[98:99]
	s_mov_b32 m0, s71
	s_nop 0
	global_load_lds_dwordx4 v66, s[98:99]
	s_mov_b32 m0, s72
	v_mfma_f32_32x32x16_bf16 v[16:31], v[118:121], v[122:125], v[16:31]
	global_load_lds_dwordx4 v68, s[98:99]
	s_mov_b32 m0, s73
	s_nop 0
	global_load_lds_dwordx4 v70, s[98:99]
	s_mov_b32 m0, s81
	v_mfma_f32_32x32x16_bf16 v[0:15], v[126:129], v[122:125], v[0:15]
	global_load_lds_dwordx4 v64, s[100:101]
	s_mov_b32 m0, s83
	s_nop 0
	global_load_lds_dwordx4 v66, s[100:101]
	s_mov_b32 m0, s88
	s_nop 0
	global_load_lds_dwordx4 v68, s[100:101]
	s_mov_b32 m0, s28
	s_nop 0
	global_load_lds_dwordx4 v70, s[100:101]
	s_add_u32 s98, s98, 0x80
	s_addc_u32 s99, s99, 0
	s_add_u32 s100, s100, 0x80
	s_addc_u32 s101, s101, 0
	ds_read_b128 v[114:117], v106
	ds_read_b128 v[118:121], v107 offset:16384
	ds_read_b128 v[122:125], v106 offset:4096
	ds_read_b128 v[126:129], v107 offset:20480
	s_waitcnt lgkmcnt(0)
	v_mfma_f32_32x32x16_bf16 v[48:63], v[118:121], v[114:117], v[48:63]
	s_mov_b32 m0, s29
	v_readfirstlane_b32 s29, v91
	v_mfma_f32_32x32x16_bf16 v[32:47], v[126:129], v[114:117], v[32:47]
	v_mfma_f32_32x32x16_bf16 v[16:31], v[118:121], v[122:125], v[16:31]
	v_mfma_f32_32x32x16_bf16 v[0:15], v[126:129], v[122:125], v[0:15]
	ds_read_b128 v[114:117], v108
	ds_read_b128 v[118:121], v109 offset:16384
	ds_read_b128 v[122:125], v108 offset:4096
	ds_read_b128 v[126:129], v109 offset:20480
	s_waitcnt lgkmcnt(0)
	v_mfma_f32_32x32x16_bf16 v[48:63], v[118:121], v[114:117], v[48:63]
	v_mfma_f32_32x32x16_bf16 v[32:47], v[126:129], v[114:117], v[32:47]
	v_mfma_f32_32x32x16_bf16 v[16:31], v[118:121], v[122:125], v[16:31]
	v_mfma_f32_32x32x16_bf16 v[0:15], v[126:129], v[122:125], v[0:15]
	ds_read_b128 v[114:117], v110
	ds_read_b128 v[118:121], v111 offset:16384
	ds_read_b128 v[122:125], v110 offset:4096
	ds_read_b128 v[126:129], v111 offset:20480
	s_waitcnt lgkmcnt(0)
	v_mfma_f32_32x32x16_bf16 v[48:63], v[118:121], v[114:117], v[48:63]
	v_mfma_f32_32x32x16_bf16 v[32:47], v[126:129], v[114:117], v[32:47]
	v_mfma_f32_32x32x16_bf16 v[16:31], v[118:121], v[122:125], v[16:31]
	v_mfma_f32_32x32x16_bf16 v[0:15], v[126:129], v[122:125], v[0:15]
	ds_read_b128 v[114:117], v112
	ds_read_b128 v[118:121], v113 offset:16384
	ds_read_b128 v[122:125], v112 offset:4096
	ds_read_b128 v[126:129], v113 offset:20480
	s_waitcnt vmcnt(0)
	s_waitcnt vmcnt(0) lgkmcnt(0)
	s_barrier
	v_mfma_f32_32x32x16_bf16 v[48:63], v[118:121], v[114:117], v[48:63]
	v_mfma_f32_32x32x16_bf16 v[32:47], v[126:129], v[114:117], v[32:47]
	global_load_lds_dwordx4 v64, s[98:99]
	s_mov_b32 m0, s84
	v_readfirstlane_b32 s84, v100
	global_load_lds_dwordx4 v66, s[98:99]
	s_mov_b32 m0, s85
	v_mfma_f32_32x32x16_bf16 v[16:31], v[118:121], v[122:125], v[16:31]
	global_load_lds_dwordx4 v68, s[98:99]
	s_mov_b32 m0, s86
	v_readfirstlane_b32 s85, v101
	global_load_lds_dwordx4 v70, s[98:99]
	s_mov_b32 m0, s87
	v_mfma_f32_32x32x16_bf16 v[0:15], v[126:129], v[122:125], v[0:15]
	global_load_lds_dwordx4 v64, s[100:101]
	s_mov_b32 m0, s89
	v_readfirstlane_b32 s86, v102
	global_load_lds_dwordx4 v66, s[100:101]
	s_mov_b32 m0, s90
	v_readfirstlane_b32 s87, v103
	global_load_lds_dwordx4 v68, s[100:101]
	s_mov_b32 m0, s91
	v_readfirstlane_b32 s89, v105
	global_load_lds_dwordx4 v70, s[100:101]
	s_add_u32 s98, s98, 0x80
	s_addc_u32 s99, s99, 0
	s_add_u32 s100, s100, 0x80
	s_addc_u32 s101, s101, 0
	ds_read_b128 v[114:117], v106 offset:32768
	ds_read_b128 v[118:121], v107 offset:49152
	ds_read_b128 v[122:125], v106 offset:36864
	ds_read_b128 v[126:129], v107 offset:53248
	s_waitcnt lgkmcnt(0)
	v_mfma_f32_32x32x16_bf16 v[48:63], v[118:121], v[114:117], v[48:63]
	s_mov_b32 m0, s70
	v_readfirstlane_b32 s70, v94
	v_mfma_f32_32x32x16_bf16 v[32:47], v[126:129], v[114:117], v[32:47]
	v_mfma_f32_32x32x16_bf16 v[16:31], v[118:121], v[122:125], v[16:31]
	v_mfma_f32_32x32x16_bf16 v[0:15], v[126:129], v[122:125], v[0:15]
	ds_read_b128 v[114:117], v108 offset:32768
	ds_read_b128 v[118:121], v109 offset:49152
	ds_read_b128 v[122:125], v108 offset:36864
	ds_read_b128 v[126:129], v109 offset:53248
	s_waitcnt lgkmcnt(0)
	v_mfma_f32_32x32x16_bf16 v[48:63], v[118:121], v[114:117], v[48:63]
	v_mfma_f32_32x32x16_bf16 v[32:47], v[126:129], v[114:117], v[32:47]
	v_mfma_f32_32x32x16_bf16 v[16:31], v[118:121], v[122:125], v[16:31]
	v_mfma_f32_32x32x16_bf16 v[0:15], v[126:129], v[122:125], v[0:15]
	ds_read_b128 v[114:117], v110 offset:32768
	ds_read_b128 v[118:121], v111 offset:49152
	ds_read_b128 v[122:125], v110 offset:36864
	ds_read_b128 v[126:129], v111 offset:53248
	s_waitcnt lgkmcnt(0)
	v_mfma_f32_32x32x16_bf16 v[48:63], v[118:121], v[114:117], v[48:63]
	v_mfma_f32_32x32x16_bf16 v[32:47], v[126:129], v[114:117], v[32:47]
	v_mfma_f32_32x32x16_bf16 v[16:31], v[118:121], v[122:125], v[16:31]
	v_mfma_f32_32x32x16_bf16 v[0:15], v[126:129], v[122:125], v[0:15]
	ds_read_b128 v[114:117], v112 offset:32768
	ds_read_b128 v[118:121], v113 offset:49152
	ds_read_b128 v[122:125], v112 offset:36864
	ds_read_b128 v[126:129], v113 offset:53248
	s_waitcnt vmcnt(0)
	s_waitcnt vmcnt(0) lgkmcnt(0)
	s_barrier
	v_mfma_f32_32x32x16_bf16 v[48:63], v[118:121], v[114:117], v[48:63]
	v_mfma_f32_32x32x16_bf16 v[32:47], v[126:129], v[114:117], v[32:47]
	global_load_lds_dwordx4 v64, s[98:99]
	s_mov_b32 m0, s71
	v_readfirstlane_b32 s71, v95
	global_load_lds_dwordx4 v66, s[98:99]
	s_mov_b32 m0, s72
	v_mfma_f32_32x32x16_bf16 v[16:31], v[118:121], v[122:125], v[16:31]
	global_load_lds_dwordx4 v68, s[98:99]
	s_mov_b32 m0, s73
	v_readfirstlane_b32 s72, v96
	global_load_lds_dwordx4 v70, s[98:99]
	s_mov_b32 m0, s81
	v_mfma_f32_32x32x16_bf16 v[0:15], v[126:129], v[122:125], v[0:15]
	global_load_lds_dwordx4 v64, s[100:101]
	s_mov_b32 m0, s83
	v_readfirstlane_b32 s73, v97
	global_load_lds_dwordx4 v66, s[100:101]
	s_mov_b32 m0, s88
	v_readfirstlane_b32 s81, v98
	global_load_lds_dwordx4 v68, s[100:101]
	s_mov_b32 m0, s28
	v_readfirstlane_b32 s28, v88
	global_load_lds_dwordx4 v70, s[100:101]
	s_add_u32 s98, s98, 0x80
	s_addc_u32 s99, s99, 0
	s_add_u32 s100, s100, 0x80
	s_addc_u32 s101, s101, 0
	ds_read_b128 v[114:117], v106
	ds_read_b128 v[118:121], v107 offset:16384
	ds_read_b128 v[122:125], v106 offset:4096
	ds_read_b128 v[126:129], v107 offset:20480
	s_waitcnt lgkmcnt(0)
	v_mfma_f32_32x32x16_bf16 v[48:63], v[118:121], v[114:117], v[48:63]
	s_mov_b32 m0, s28
	v_readfirstlane_b32 s83, v99
	v_readfirstlane_b32 s88, v104
	v_mfma_f32_32x32x16_bf16 v[32:47], v[126:129], v[114:117], v[32:47]
	v_mfma_f32_32x32x16_bf16 v[16:31], v[118:121], v[122:125], v[16:31]
	v_mfma_f32_32x32x16_bf16 v[0:15], v[126:129], v[122:125], v[0:15]
	ds_read_b128 v[114:117], v108
	ds_read_b128 v[118:121], v109 offset:16384
	ds_read_b128 v[122:125], v108 offset:4096
	ds_read_b128 v[126:129], v109 offset:20480
	s_waitcnt lgkmcnt(0)
	v_mfma_f32_32x32x16_bf16 v[48:63], v[118:121], v[114:117], v[48:63]
	v_mfma_f32_32x32x16_bf16 v[32:47], v[126:129], v[114:117], v[32:47]
	v_mfma_f32_32x32x16_bf16 v[16:31], v[118:121], v[122:125], v[16:31]
	v_mfma_f32_32x32x16_bf16 v[0:15], v[126:129], v[122:125], v[0:15]
	ds_read_b128 v[114:117], v110
	ds_read_b128 v[118:121], v111 offset:16384
	ds_read_b128 v[122:125], v110 offset:4096
	ds_read_b128 v[126:129], v111 offset:20480
	s_waitcnt lgkmcnt(0)
	v_mfma_f32_32x32x16_bf16 v[48:63], v[118:121], v[114:117], v[48:63]
	v_mfma_f32_32x32x16_bf16 v[32:47], v[126:129], v[114:117], v[32:47]
	v_mfma_f32_32x32x16_bf16 v[16:31], v[118:121], v[122:125], v[16:31]
	v_mfma_f32_32x32x16_bf16 v[0:15], v[126:129], v[122:125], v[0:15]
	ds_read_b128 v[114:117], v112
	ds_read_b128 v[118:121], v113 offset:16384
	ds_read_b128 v[122:125], v112 offset:4096
	ds_read_b128 v[126:129], v113 offset:20480
	s_waitcnt vmcnt(0)
	s_waitcnt vmcnt(0) lgkmcnt(0)
	s_barrier
	v_mfma_f32_32x32x16_bf16 v[48:63], v[118:121], v[114:117], v[48:63]
	v_mfma_f32_32x32x16_bf16 v[32:47], v[126:129], v[114:117], v[32:47]
	global_load_lds_dwordx4 v64, s[98:99]
	s_mov_b32 m0, s29
	s_nop 0
	global_load_lds_dwordx4 v66, s[98:99]
	s_mov_b32 m0, s34
	v_mfma_f32_32x32x16_bf16 v[16:31], v[118:121], v[122:125], v[16:31]
	global_load_lds_dwordx4 v68, s[98:99]
	s_mov_b32 m0, s35
	s_nop 0
	global_load_lds_dwordx4 v70, s[98:99]
	s_mov_b32 m0, s70
	v_mfma_f32_32x32x16_bf16 v[0:15], v[126:129], v[122:125], v[0:15]
	global_load_lds_dwordx4 v64, s[100:101]
	s_mov_b32 m0, s71
	s_nop 0
	global_load_lds_dwordx4 v66, s[100:101]
	s_mov_b32 m0, s72
	s_nop 0
	global_load_lds_dwordx4 v68, s[100:101]
	s_mov_b32 m0, s73
	s_nop 0
	global_load_lds_dwordx4 v70, s[100:101]
	s_add_u32 s98, s98, 0x80
	s_addc_u32 s99, s99, 0
	s_add_u32 s100, s100, 0x80
	s_addc_u32 s101, s101, 0
	ds_read_b128 v[114:117], v106 offset:32768
	ds_read_b128 v[118:121], v107 offset:49152
	ds_read_b128 v[122:125], v106 offset:36864
	ds_read_b128 v[126:129], v107 offset:53248
	s_waitcnt lgkmcnt(0)
	v_mfma_f32_32x32x16_bf16 v[48:63], v[118:121], v[114:117], v[48:63]
	s_mov_b32 m0, s81
	v_mfma_f32_32x32x16_bf16 v[32:47], v[126:129], v[114:117], v[32:47]
	v_mfma_f32_32x32x16_bf16 v[16:31], v[118:121], v[122:125], v[16:31]
	v_mfma_f32_32x32x16_bf16 v[0:15], v[126:129], v[122:125], v[0:15]
	ds_read_b128 v[114:117], v108 offset:32768
	ds_read_b128 v[118:121], v109 offset:49152
	ds_read_b128 v[122:125], v108 offset:36864
	ds_read_b128 v[126:129], v109 offset:53248
	s_waitcnt lgkmcnt(0)
	v_mfma_f32_32x32x16_bf16 v[48:63], v[118:121], v[114:117], v[48:63]
	v_mfma_f32_32x32x16_bf16 v[32:47], v[126:129], v[114:117], v[32:47]
	v_mfma_f32_32x32x16_bf16 v[16:31], v[118:121], v[122:125], v[16:31]
	v_mfma_f32_32x32x16_bf16 v[0:15], v[126:129], v[122:125], v[0:15]
	ds_read_b128 v[114:117], v110 offset:32768
	ds_read_b128 v[118:121], v111 offset:49152
	ds_read_b128 v[122:125], v110 offset:36864
	ds_read_b128 v[126:129], v111 offset:53248
	s_waitcnt lgkmcnt(0)
	v_mfma_f32_32x32x16_bf16 v[48:63], v[118:121], v[114:117], v[48:63]
	v_mfma_f32_32x32x16_bf16 v[32:47], v[126:129], v[114:117], v[32:47]
	v_mfma_f32_32x32x16_bf16 v[16:31], v[118:121], v[122:125], v[16:31]
	v_mfma_f32_32x32x16_bf16 v[0:15], v[126:129], v[122:125], v[0:15]
	ds_read_b128 v[114:117], v112 offset:32768
	ds_read_b128 v[118:121], v113 offset:49152
	ds_read_b128 v[122:125], v112 offset:36864
	ds_read_b128 v[126:129], v113 offset:53248
	s_waitcnt vmcnt(0)
	s_waitcnt vmcnt(0) lgkmcnt(0)
	s_barrier
	v_mfma_f32_32x32x16_bf16 v[48:63], v[118:121], v[114:117], v[48:63]
	v_mfma_f32_32x32x16_bf16 v[32:47], v[126:129], v[114:117], v[32:47]
	global_load_lds_dwordx4 v64, s[98:99]
	s_mov_b32 m0, s83
	s_nop 0
	global_load_lds_dwordx4 v66, s[98:99]
	s_mov_b32 m0, s84
	v_mfma_f32_32x32x16_bf16 v[16:31], v[118:121], v[122:125], v[16:31]
	global_load_lds_dwordx4 v68, s[98:99]
	s_mov_b32 m0, s85
	s_nop 0
	global_load_lds_dwordx4 v70, s[98:99]
	s_mov_b32 m0, s86
	v_mfma_f32_32x32x16_bf16 v[0:15], v[126:129], v[122:125], v[0:15]
	global_load_lds_dwordx4 v64, s[100:101]
	s_mov_b32 m0, s87
	s_nop 0
	global_load_lds_dwordx4 v66, s[100:101]
	s_mov_b32 m0, s88
	s_nop 0
	global_load_lds_dwordx4 v68, s[100:101]
	s_mov_b32 m0, s89
	s_nop 0
	global_load_lds_dwordx4 v70, s[100:101]
	s_add_u32 s98, s98, 0x80
	s_addc_u32 s99, s99, 0
	s_add_u32 s100, s100, 0x80
	s_addc_u32 s101, s101, 0
	ds_read_b128 v[114:117], v106
	ds_read_b128 v[118:121], v107 offset:16384
	ds_read_b128 v[122:125], v106 offset:4096
	ds_read_b128 v[126:129], v107 offset:20480
	s_waitcnt lgkmcnt(0)
	v_mfma_f32_32x32x16_bf16 v[48:63], v[118:121], v[114:117], v[48:63]
	s_mov_b32 m0, s28
	v_mfma_f32_32x32x16_bf16 v[32:47], v[126:129], v[114:117], v[32:47]
	v_mfma_f32_32x32x16_bf16 v[16:31], v[118:121], v[122:125], v[16:31]
	v_mfma_f32_32x32x16_bf16 v[0:15], v[126:129], v[122:125], v[0:15]
	ds_read_b128 v[114:117], v108
	ds_read_b128 v[118:121], v109 offset:16384
	ds_read_b128 v[122:125], v108 offset:4096
	ds_read_b128 v[126:129], v109 offset:20480
	s_waitcnt lgkmcnt(0)
	v_mfma_f32_32x32x16_bf16 v[48:63], v[118:121], v[114:117], v[48:63]
	v_mfma_f32_32x32x16_bf16 v[32:47], v[126:129], v[114:117], v[32:47]
	v_mfma_f32_32x32x16_bf16 v[16:31], v[118:121], v[122:125], v[16:31]
	v_mfma_f32_32x32x16_bf16 v[0:15], v[126:129], v[122:125], v[0:15]
	ds_read_b128 v[114:117], v110
	ds_read_b128 v[118:121], v111 offset:16384
	ds_read_b128 v[122:125], v110 offset:4096
	ds_read_b128 v[126:129], v111 offset:20480
	s_waitcnt lgkmcnt(0)
	v_mfma_f32_32x32x16_bf16 v[48:63], v[118:121], v[114:117], v[48:63]
	v_mfma_f32_32x32x16_bf16 v[32:47], v[126:129], v[114:117], v[32:47]
	v_mfma_f32_32x32x16_bf16 v[16:31], v[118:121], v[122:125], v[16:31]
	v_mfma_f32_32x32x16_bf16 v[0:15], v[126:129], v[122:125], v[0:15]
	ds_read_b128 v[114:117], v112
	ds_read_b128 v[118:121], v113 offset:16384
	ds_read_b128 v[122:125], v112 offset:4096
	ds_read_b128 v[126:129], v113 offset:20480
	s_waitcnt vmcnt(0)
	s_waitcnt vmcnt(0) lgkmcnt(0)
	s_barrier
	v_mfma_f32_32x32x16_bf16 v[48:63], v[118:121], v[114:117], v[48:63]
	v_mfma_f32_32x32x16_bf16 v[32:47], v[126:129], v[114:117], v[32:47]
	global_load_lds_dwordx4 v64, s[98:99]
	s_mov_b32 m0, s29
	s_nop 0
	global_load_lds_dwordx4 v66, s[98:99]
	s_mov_b32 m0, s34
	v_mfma_f32_32x32x16_bf16 v[16:31], v[118:121], v[122:125], v[16:31]
	global_load_lds_dwordx4 v68, s[98:99]
	s_mov_b32 m0, s35
	s_nop 0
	global_load_lds_dwordx4 v70, s[98:99]
	s_mov_b32 m0, s70
	v_mfma_f32_32x32x16_bf16 v[0:15], v[126:129], v[122:125], v[0:15]
	global_load_lds_dwordx4 v64, s[100:101]
	s_mov_b32 m0, s71
	s_nop 0
	global_load_lds_dwordx4 v66, s[100:101]
	s_mov_b32 m0, s72
	s_nop 0
	global_load_lds_dwordx4 v68, s[100:101]
	s_mov_b32 m0, s73
	s_nop 0
	global_load_lds_dwordx4 v70, s[100:101]
	s_add_u32 s98, s98, 0x80
	s_addc_u32 s99, s99, 0
	s_add_u32 s100, s100, 0x80
	s_addc_u32 s101, s101, 0
	ds_read_b128 v[114:117], v106 offset:32768
	ds_read_b128 v[118:121], v107 offset:49152
	ds_read_b128 v[122:125], v106 offset:36864
	ds_read_b128 v[126:129], v107 offset:53248
	s_waitcnt lgkmcnt(0)
	v_mfma_f32_32x32x16_bf16 v[48:63], v[118:121], v[114:117], v[48:63]
	s_mov_b32 m0, s81
	v_mfma_f32_32x32x16_bf16 v[32:47], v[126:129], v[114:117], v[32:47]
	v_mfma_f32_32x32x16_bf16 v[16:31], v[118:121], v[122:125], v[16:31]
	v_mfma_f32_32x32x16_bf16 v[0:15], v[126:129], v[122:125], v[0:15]
	ds_read_b128 v[114:117], v108 offset:32768
	ds_read_b128 v[118:121], v109 offset:49152
	ds_read_b128 v[122:125], v108 offset:36864
	ds_read_b128 v[126:129], v109 offset:53248
	s_waitcnt lgkmcnt(0)
	v_mfma_f32_32x32x16_bf16 v[48:63], v[118:121], v[114:117], v[48:63]
	v_mfma_f32_32x32x16_bf16 v[32:47], v[126:129], v[114:117], v[32:47]
	v_mfma_f32_32x32x16_bf16 v[16:31], v[118:121], v[122:125], v[16:31]
	v_mfma_f32_32x32x16_bf16 v[0:15], v[126:129], v[122:125], v[0:15]
	ds_read_b128 v[114:117], v110 offset:32768
	ds_read_b128 v[118:121], v111 offset:49152
	ds_read_b128 v[122:125], v110 offset:36864
	ds_read_b128 v[126:129], v111 offset:53248
	s_waitcnt lgkmcnt(0)
	v_mfma_f32_32x32x16_bf16 v[48:63], v[118:121], v[114:117], v[48:63]
	v_mfma_f32_32x32x16_bf16 v[32:47], v[126:129], v[114:117], v[32:47]
	v_mfma_f32_32x32x16_bf16 v[16:31], v[118:121], v[122:125], v[16:31]
	v_mfma_f32_32x32x16_bf16 v[0:15], v[126:129], v[122:125], v[0:15]
	ds_read_b128 v[114:117], v112 offset:32768
	ds_read_b128 v[118:121], v113 offset:49152
	ds_read_b128 v[122:125], v112 offset:36864
	ds_read_b128 v[126:129], v113 offset:53248
	s_waitcnt vmcnt(0)
	s_waitcnt vmcnt(0) lgkmcnt(0)
	s_barrier
	v_mfma_f32_32x32x16_bf16 v[48:63], v[118:121], v[114:117], v[48:63]
	v_mfma_f32_32x32x16_bf16 v[32:47], v[126:129], v[114:117], v[32:47]
	global_load_lds_dwordx4 v64, s[98:99]
	s_mov_b32 m0, s83
	s_nop 0
	global_load_lds_dwordx4 v66, s[98:99]
	s_mov_b32 m0, s84
	v_mfma_f32_32x32x16_bf16 v[16:31], v[118:121], v[122:125], v[16:31]
	global_load_lds_dwordx4 v68, s[98:99]
	s_mov_b32 m0, s85
	s_nop 0
	global_load_lds_dwordx4 v70, s[98:99]
	s_mov_b32 m0, s86
	v_mfma_f32_32x32x16_bf16 v[0:15], v[126:129], v[122:125], v[0:15]
	global_load_lds_dwordx4 v64, s[100:101]
	s_mov_b32 m0, s87
	s_nop 0
	global_load_lds_dwordx4 v66, s[100:101]
	s_mov_b32 m0, s88
	s_nop 0
	global_load_lds_dwordx4 v68, s[100:101]
	s_mov_b32 m0, s89
	s_nop 0
	global_load_lds_dwordx4 v70, s[100:101]
	s_add_u32 s98, s98, 0x80
	s_addc_u32 s99, s99, 0
	s_add_u32 s100, s100, 0x80
	s_addc_u32 s101, s101, 0
	ds_read_b128 v[114:117], v106
	ds_read_b128 v[118:121], v107 offset:16384
	ds_read_b128 v[122:125], v106 offset:4096
	ds_read_b128 v[126:129], v107 offset:20480
	s_waitcnt lgkmcnt(0)
	v_mfma_f32_32x32x16_bf16 v[48:63], v[118:121], v[114:117], v[48:63]
	s_mov_b32 m0, s28
	v_mfma_f32_32x32x16_bf16 v[32:47], v[126:129], v[114:117], v[32:47]
	v_mfma_f32_32x32x16_bf16 v[16:31], v[118:121], v[122:125], v[16:31]
	v_mfma_f32_32x32x16_bf16 v[0:15], v[126:129], v[122:125], v[0:15]
	ds_read_b128 v[114:117], v108
	ds_read_b128 v[118:121], v109 offset:16384
	ds_read_b128 v[122:125], v108 offset:4096
	ds_read_b128 v[126:129], v109 offset:20480
	s_waitcnt lgkmcnt(0)
	v_mfma_f32_32x32x16_bf16 v[48:63], v[118:121], v[114:117], v[48:63]
	v_mfma_f32_32x32x16_bf16 v[32:47], v[126:129], v[114:117], v[32:47]
	v_mfma_f32_32x32x16_bf16 v[16:31], v[118:121], v[122:125], v[16:31]
	v_mfma_f32_32x32x16_bf16 v[0:15], v[126:129], v[122:125], v[0:15]
	ds_read_b128 v[114:117], v110
	ds_read_b128 v[118:121], v111 offset:16384
	ds_read_b128 v[122:125], v110 offset:4096
	ds_read_b128 v[126:129], v111 offset:20480
	s_waitcnt lgkmcnt(0)
	v_mfma_f32_32x32x16_bf16 v[48:63], v[118:121], v[114:117], v[48:63]
	v_mfma_f32_32x32x16_bf16 v[32:47], v[126:129], v[114:117], v[32:47]
	v_mfma_f32_32x32x16_bf16 v[16:31], v[118:121], v[122:125], v[16:31]
	v_mfma_f32_32x32x16_bf16 v[0:15], v[126:129], v[122:125], v[0:15]
	ds_read_b128 v[114:117], v112
	ds_read_b128 v[118:121], v113 offset:16384
	ds_read_b128 v[122:125], v112 offset:4096
	ds_read_b128 v[126:129], v113 offset:20480
	s_waitcnt vmcnt(0)
	s_waitcnt vmcnt(0) lgkmcnt(0)
	s_barrier
	v_mfma_f32_32x32x16_bf16 v[48:63], v[118:121], v[114:117], v[48:63]
	v_mfma_f32_32x32x16_bf16 v[32:47], v[126:129], v[114:117], v[32:47]
	global_load_lds_dwordx4 v64, s[98:99]
	s_mov_b32 m0, s29
	s_nop 0
	global_load_lds_dwordx4 v66, s[98:99]
	s_mov_b32 m0, s34
	v_mfma_f32_32x32x16_bf16 v[16:31], v[118:121], v[122:125], v[16:31]
	global_load_lds_dwordx4 v68, s[98:99]
	s_mov_b32 m0, s35
	s_nop 0
	global_load_lds_dwordx4 v70, s[98:99]
	s_mov_b32 m0, s70
	v_mfma_f32_32x32x16_bf16 v[0:15], v[126:129], v[122:125], v[0:15]
	global_load_lds_dwordx4 v64, s[100:101]
	s_mov_b32 m0, s71
	s_nop 0
	global_load_lds_dwordx4 v66, s[100:101]
	s_mov_b32 m0, s72
	s_nop 0
	global_load_lds_dwordx4 v68, s[100:101]
	s_mov_b32 m0, s73
	s_nop 0
	global_load_lds_dwordx4 v70, s[100:101]
	s_add_u32 s98, s98, 0x80
	s_addc_u32 s99, s99, 0
	s_add_u32 s100, s100, 0x80
	s_addc_u32 s101, s101, 0
	ds_read_b128 v[114:117], v106 offset:32768
	ds_read_b128 v[118:121], v107 offset:49152
	ds_read_b128 v[122:125], v106 offset:36864
	ds_read_b128 v[126:129], v107 offset:53248
	s_waitcnt lgkmcnt(0)
	v_mfma_f32_32x32x16_bf16 v[16:31], v[118:121], v[122:125], v[16:31]
	s_mov_b32 m0, s81
	v_mfma_f32_32x32x16_bf16 v[0:15], v[126:129], v[122:125], v[0:15]
	v_mfma_f32_32x32x16_bf16 v[32:47], v[126:129], v[114:117], v[32:47]
	v_mfma_f32_32x32x16_bf16 v[48:63], v[118:121], v[114:117], v[48:63]
	ds_read_b128 v[114:117], v108 offset:32768
	ds_read_b128 v[118:121], v109 offset:49152
	ds_read_b128 v[122:125], v108 offset:36864
	ds_read_b128 v[126:129], v109 offset:53248
	s_waitcnt lgkmcnt(0)
	v_mfma_f32_32x32x16_bf16 v[16:31], v[118:121], v[122:125], v[16:31]
	v_mfma_f32_32x32x16_bf16 v[0:15], v[126:129], v[122:125], v[0:15]
	v_mfma_f32_32x32x16_bf16 v[32:47], v[126:129], v[114:117], v[32:47]
	v_mfma_f32_32x32x16_bf16 v[48:63], v[118:121], v[114:117], v[48:63]
	ds_read_b128 v[114:117], v110 offset:32768
	ds_read_b128 v[118:121], v111 offset:49152
	ds_read_b128 v[122:125], v110 offset:36864
	ds_read_b128 v[126:129], v111 offset:53248
	s_waitcnt lgkmcnt(0)
	v_mfma_f32_32x32x16_bf16 v[16:31], v[118:121], v[122:125], v[16:31]
	v_mfma_f32_32x32x16_bf16 v[0:15], v[126:129], v[122:125], v[0:15]
	v_mfma_f32_32x32x16_bf16 v[32:47], v[126:129], v[114:117], v[32:47]
	v_mfma_f32_32x32x16_bf16 v[48:63], v[118:121], v[114:117], v[48:63]
	ds_read_b128 v[114:117], v112 offset:32768
	ds_read_b128 v[118:121], v113 offset:49152
	ds_read_b128 v[122:125], v112 offset:36864
	ds_read_b128 v[126:129], v113 offset:53248
	s_waitcnt vmcnt(0)
	s_waitcnt vmcnt(0) lgkmcnt(0)
	s_barrier
	global_load_lds_dwordx4 v64, s[98:99]
	s_mov_b32 m0, s83
	v_mfma_f32_32x32x16_bf16 v[16:31], v[118:121], v[122:125], v[16:31]
	global_load_lds_dwordx4 v66, s[98:99]
	s_mov_b32 m0, s84
	s_nop 0
	global_load_lds_dwordx4 v68, s[98:99]
	s_mov_b32 m0, s85
	v_mfma_f32_32x32x16_bf16 v[0:15], v[126:129], v[122:125], v[0:15]
	global_load_lds_dwordx4 v70, s[98:99]
	s_mov_b32 m0, s86
	s_nop 0
	global_load_lds_dwordx4 v64, s[100:101]
	s_mov_b32 m0, s87
	v_mfma_f32_32x32x16_bf16 v[32:47], v[126:129], v[114:117], v[32:47]
	global_load_lds_dwordx4 v66, s[100:101]
	s_mov_b32 m0, s88
	s_nop 0
	global_load_lds_dwordx4 v68, s[100:101]
	s_mov_b32 m0, s89
	v_mfma_f32_32x32x16_bf16 v[48:63], v[118:121], v[114:117], v[48:63]
	global_load_lds_dwordx4 v70, s[100:101]
	ds_read_b128 v[72:75], v106
	ds_read_b128 v[76:79], v107 offset:16384
	ds_read_b128 v[80:83], v106 offset:4096
	ds_read_b128 v[84:87], v107 offset:20480
	s_waitcnt lgkmcnt(0)
	v_mfma_f32_32x32x16_bf16 v[16:31], v[76:79], v[80:83], v[16:31]
	v_mfma_f32_32x32x16_bf16 v[0:15], v[84:87], v[80:83], v[0:15]
	v_mfma_f32_32x32x16_bf16 v[32:47], v[84:87], v[72:75], v[32:47]
	v_mfma_f32_32x32x16_bf16 v[48:63], v[76:79], v[72:75], v[48:63]
	ds_read_b128 v[72:75], v108
	ds_read_b128 v[76:79], v109 offset:16384
	ds_read_b128 v[80:83], v108 offset:4096
	ds_read_b128 v[84:87], v109 offset:20480
	s_waitcnt lgkmcnt(0)
	v_mfma_f32_32x32x16_bf16 v[16:31], v[76:79], v[80:83], v[16:31]
	v_mfma_f32_32x32x16_bf16 v[0:15], v[84:87], v[80:83], v[0:15]
	v_mfma_f32_32x32x16_bf16 v[32:47], v[84:87], v[72:75], v[32:47]
	v_mfma_f32_32x32x16_bf16 v[48:63], v[76:79], v[72:75], v[48:63]
	ds_read_b128 v[72:75], v110
	ds_read_b128 v[76:79], v111 offset:16384
	ds_read_b128 v[80:83], v110 offset:4096
	ds_read_b128 v[84:87], v111 offset:20480
	s_waitcnt lgkmcnt(0)
	v_mfma_f32_32x32x16_bf16 v[16:31], v[76:79], v[80:83], v[16:31]
	v_mfma_f32_32x32x16_bf16 v[0:15], v[84:87], v[80:83], v[0:15]
	v_mfma_f32_32x32x16_bf16 v[32:47], v[84:87], v[72:75], v[32:47]
	v_mfma_f32_32x32x16_bf16 v[48:63], v[76:79], v[72:75], v[48:63]
	ds_read_b128 v[72:75], v112
	ds_read_b128 v[76:79], v113 offset:16384
	ds_read_b128 v[80:83], v112 offset:4096
	ds_read_b128 v[84:87], v113 offset:20480
	s_waitcnt vmcnt(0)
	s_waitcnt vmcnt(0) lgkmcnt(0)
	s_barrier
	v_mfma_f32_32x32x16_bf16 v[16:31], v[76:79], v[80:83], v[16:31]
	v_mfma_f32_32x32x16_bf16 v[0:15], v[84:87], v[80:83], v[0:15]
	v_mfma_f32_32x32x16_bf16 v[32:47], v[84:87], v[72:75], v[32:47]
	v_mfma_f32_32x32x16_bf16 v[48:63], v[76:79], v[72:75], v[48:63]
	ds_read_b128 v[72:75], v113 offset:53248
	ds_read_b128 v[76:79], v112 offset:36864
	ds_read_b128 v[80:83], v113 offset:49152
	ds_read_b128 v[84:87], v112 offset:32768
	ds_read_b128 v[114:117], v111 offset:53248
	ds_read_b128 v[118:121], v110 offset:36864
	ds_read_b128 v[122:125], v111 offset:49152
	ds_read_b128 v[126:129], v110 offset:32768
	ds_read_b128 v[130:133], v109 offset:53248
	ds_read_b128 v[134:137], v108 offset:36864
	ds_read_b128 v[138:141], v109 offset:49152
	ds_read_b128 v[142:145], v108 offset:32768
	ds_read_b128 v[146:149], v107 offset:53248
	ds_read_b128 v[150:153], v106 offset:36864
	ds_read_b128 v[156:159], v107 offset:49152
	ds_read_b128 v[160:163], v106 offset:32768
	s_waitcnt vmcnt(0)
	s_waitcnt lgkmcnt(0)
	s_barrier
	v_mfma_f32_32x32x16_bf16 v[16:31], v[156:159], v[150:153], v[16:31]
	v_mfma_f32_32x32x16_bf16 v[0:15], v[146:149], v[150:153], v[0:15]
	v_mfma_f32_32x32x16_bf16 v[32:47], v[146:149], v[160:163], v[32:47]
	v_mfma_f32_32x32x16_bf16 v[48:63], v[156:159], v[160:163], v[48:63]
	v_mfma_f32_32x32x16_bf16 v[16:31], v[138:141], v[134:137], v[16:31]
	v_mfma_f32_32x32x16_bf16 v[0:15], v[130:133], v[134:137], v[0:15]
	v_mfma_f32_32x32x16_bf16 v[32:47], v[130:133], v[142:145], v[32:47]
	v_mfma_f32_32x32x16_bf16 v[48:63], v[138:141], v[142:145], v[48:63]
	v_mfma_f32_32x32x16_bf16 v[16:31], v[122:125], v[118:121], v[16:31]
	v_mfma_f32_32x32x16_bf16 v[0:15], v[114:117], v[118:121], v[0:15]
	v_mfma_f32_32x32x16_bf16 v[32:47], v[114:117], v[126:129], v[32:47]
	v_mfma_f32_32x32x16_bf16 v[48:63], v[122:125], v[126:129], v[48:63]
	v_mfma_f32_32x32x16_bf16 v[16:31], v[80:83], v[76:79], v[16:31]
	v_mfma_f32_32x32x16_bf16 v[0:15], v[72:75], v[76:79], v[0:15]
	v_add_u32_e32 v76, s80, v89
	v_ashrrev_i32_e32 v77, 31, v76
	v_mfma_f32_32x32x16_bf16 v[32:47], v[72:75], v[84:87], v[32:47]
	v_or_b32_e32 v72, s82, v90
	v_lshlrev_b64 v[74:75], 12, v[76:77]
	v_ashrrev_i32_e32 v73, 31, v72
	v_lshl_add_u64 v[78:79], s[40:41], 0, v[74:75]
	v_mfma_f32_32x32x16_bf16 v[48:63], v[80:83], v[84:87], v[48:63]
	v_lshlrev_b64 v[82:83], 2, v[72:73]
	v_lshl_add_u64 v[78:79], v[78:79], 0, v[82:83]
	v_lshl_add_u64 v[80:81], s[38:39], 0, v[74:75]
	v_lshl_add_u64 v[228:229], v[80:81], 0, v[82:83]
	v_or_b32_e32 v234, 32, v76
	v_ashrrev_i32_e32 v235, 31, v234
	v_lshlrev_b64 v[234:235], 12, v[234:235]
	v_lshl_add_u64 v[230:231], s[40:41], 0, v[234:235]
	v_lshl_add_u64 v[230:231], v[230:231], 0, v[82:83]
	v_lshl_add_u64 v[232:233], s[38:39], 0, v[234:235]
	v_lshl_add_u64 v[232:233], v[232:233], 0, v[82:83]
	global_load_dwordx4 v[164:167], v[78:79], off
	global_load_dwordx4 v[168:171], v[78:79], off offset:32
	global_load_dwordx4 v[172:175], v[78:79], off offset:64
	global_load_dwordx4 v[176:179], v[78:79], off offset:96
	global_load_dwordx4 v[180:183], v[78:79], off offset:128
	global_load_dwordx4 v[184:187], v[78:79], off offset:160
	global_load_dwordx4 v[188:191], v[78:79], off offset:192
	global_load_dwordx4 v[192:195], v[78:79], off offset:224
	global_load_dwordx4 v[196:199], v[230:231], off
	global_load_dwordx4 v[200:203], v[230:231], off offset:32
	global_load_dwordx4 v[204:207], v[230:231], off offset:64
	global_load_dwordx4 v[208:211], v[230:231], off offset:96
	global_load_dwordx4 v[212:215], v[230:231], off offset:128
	global_load_dwordx4 v[216:219], v[230:231], off offset:160
	global_load_dwordx4 v[220:223], v[230:231], off offset:192
	global_load_dwordx4 v[224:227], v[230:231], off offset:224
	s_waitcnt vmcnt(15)
	v_pk_fma_f32 v[166:167], v[166:167], s[78:79], v[50:51] op_sel_hi:[1,0,1]
	v_pk_fma_f32 v[164:165], v[164:165], s[78:79], v[48:49] op_sel_hi:[1,0,1]
	global_store_dwordx4 v[228:229], v[164:167], off
	s_waitcnt vmcnt(15)
	v_pk_fma_f32 v[168:169], v[168:169], s[78:79], v[52:53] op_sel_hi:[1,0,1]
	v_pk_fma_f32 v[170:171], v[170:171], s[78:79], v[54:55] op_sel_hi:[1,0,1]
	global_store_dwordx4 v[228:229], v[168:171], off offset:32
	s_waitcnt vmcnt(15)
	v_pk_fma_f32 v[172:173], v[172:173], s[78:79], v[56:57] op_sel_hi:[1,0,1]
	v_pk_fma_f32 v[174:175], v[174:175], s[78:79], v[58:59] op_sel_hi:[1,0,1]
	global_store_dwordx4 v[228:229], v[172:175], off offset:64
	s_waitcnt vmcnt(15)
	v_pk_fma_f32 v[176:177], v[176:177], s[78:79], v[60:61] op_sel_hi:[1,0,1]
	v_pk_fma_f32 v[178:179], v[178:179], s[78:79], v[62:63] op_sel_hi:[1,0,1]
	global_store_dwordx4 v[228:229], v[176:179], off offset:96
	s_waitcnt vmcnt(15)
	v_pk_fma_f32 v[182:183], v[182:183], s[78:79], v[34:35] op_sel_hi:[1,0,1]
	v_pk_fma_f32 v[180:181], v[180:181], s[78:79], v[32:33] op_sel_hi:[1,0,1]
	global_store_dwordx4 v[228:229], v[180:183], off offset:128
	s_waitcnt vmcnt(15)
	v_pk_fma_f32 v[184:185], v[184:185], s[78:79], v[36:37] op_sel_hi:[1,0,1]
	v_pk_fma_f32 v[186:187], v[186:187], s[78:79], v[38:39] op_sel_hi:[1,0,1]
	global_store_dwordx4 v[228:229], v[184:187], off offset:160
	s_waitcnt vmcnt(15)
	v_pk_fma_f32 v[188:189], v[188:189], s[78:79], v[40:41] op_sel_hi:[1,0,1]
	v_pk_fma_f32 v[190:191], v[190:191], s[78:79], v[42:43] op_sel_hi:[1,0,1]
	global_store_dwordx4 v[228:229], v[188:191], off offset:192
	s_waitcnt vmcnt(15)
	v_pk_fma_f32 v[192:193], v[192:193], s[78:79], v[44:45] op_sel_hi:[1,0,1]
	v_pk_fma_f32 v[194:195], v[194:195], s[78:79], v[46:47] op_sel_hi:[1,0,1]
	global_store_dwordx4 v[228:229], v[192:195], off offset:224
	s_waitcnt vmcnt(15)
	v_pk_fma_f32 v[198:199], v[198:199], s[78:79], v[18:19] op_sel_hi:[1,0,1]
	v_pk_fma_f32 v[196:197], v[196:197], s[78:79], v[16:17] op_sel_hi:[1,0,1]
	global_store_dwordx4 v[232:233], v[196:199], off
	s_waitcnt vmcnt(15)
	v_pk_fma_f32 v[200:201], v[200:201], s[78:79], v[20:21] op_sel_hi:[1,0,1]
	v_pk_fma_f32 v[202:203], v[202:203], s[78:79], v[22:23] op_sel_hi:[1,0,1]
	global_store_dwordx4 v[232:233], v[200:203], off offset:32
	s_waitcnt vmcnt(15)
	v_pk_fma_f32 v[204:205], v[204:205], s[78:79], v[24:25] op_sel_hi:[1,0,1]
	v_pk_fma_f32 v[206:207], v[206:207], s[78:79], v[26:27] op_sel_hi:[1,0,1]
	global_store_dwordx4 v[232:233], v[204:207], off offset:64
	s_waitcnt vmcnt(15)
	v_pk_fma_f32 v[208:209], v[208:209], s[78:79], v[28:29] op_sel_hi:[1,0,1]
	v_pk_fma_f32 v[210:211], v[210:211], s[78:79], v[30:31] op_sel_hi:[1,0,1]
	global_store_dwordx4 v[232:233], v[208:211], off offset:96
	s_waitcnt vmcnt(15)
	v_pk_fma_f32 v[214:215], v[214:215], s[78:79], v[2:3] op_sel_hi:[1,0,1]
	v_pk_fma_f32 v[212:213], v[212:213], s[78:79], v[0:1] op_sel_hi:[1,0,1]
	global_store_dwordx4 v[232:233], v[212:215], off offset:128
	s_waitcnt vmcnt(15)
	v_pk_fma_f32 v[216:217], v[216:217], s[78:79], v[4:5] op_sel_hi:[1,0,1]
	v_pk_fma_f32 v[218:219], v[218:219], s[78:79], v[6:7] op_sel_hi:[1,0,1]
	global_store_dwordx4 v[232:233], v[216:219], off offset:160
	s_waitcnt vmcnt(15)
	v_pk_fma_f32 v[220:221], v[220:221], s[78:79], v[8:9] op_sel_hi:[1,0,1]
	v_pk_fma_f32 v[222:223], v[222:223], s[78:79], v[10:11] op_sel_hi:[1,0,1]
	global_store_dwordx4 v[232:233], v[220:223], off offset:192
	s_waitcnt vmcnt(15)
	v_pk_fma_f32 v[224:225], v[224:225], s[78:79], v[12:13] op_sel_hi:[1,0,1]
	v_pk_fma_f32 v[226:227], v[226:227], s[78:79], v[14:15] op_sel_hi:[1,0,1]
	global_store_dwordx4 v[232:233], v[224:227], off offset:224
	s_add_i32 s79, s79, s33
	s_add_i32 s28, s2, s79
	s_cmpk_lt_i32 s28, 0x400
	s_cbranch_scc0 .LBB0_564
